# v34 + rstd via v_rsq_f32 in the transposed-V epilogue (32 per unit), router LayerNorm and final LayerNorm
# baseline (speedup 1.0000x reference)
; __device__ __forceinline__ float clamp448(float x) { return __builtin_amdgcn_fmed3f(x, -448.0f, 448.0f); }
; __device__ __forceinline__ float rms_scale(const float* ssq, int row, int which) {
;     const f32x4 a = *(const f32x4*)(ssq + (size_t)row * 16 + which * 8), b = *(const f32x4*)(ssq + (size_t)row * 16 + which * 8 + 4);
;     const float s = ((a[0] + a[1]) + (a[2] + a[3])) + ((b[0] + b[1]) + (b[2] + b[3]));
;     return 1.0f / sqrtf(s * (1.0f / 512.0f) + RMS_EPS);
;     __device__ __forceinline__ void operator()(EPI_ARGS) const {
;     ...
;             for (int m = 0; m < 4; ++m) { const int t0 = u.pm * BM + ai * HALF + wr * 64 + 16 * m + 4 * fq, q = 4 * m + fq;
;                 const f32x4 rs = (f32x4){rms_scale(ssq, t0, 1), rms_scale(ssq, t0 + 1, 1), rms_scale(ssq, t0 + 2, 1), rms_scale(ssq, t0 + 3, 1)} * osc;
;                 const size_t tpos = (size_t)(t0 & ~63) + 32 * (q & 1) + 16 * (q >> 3) + 4 * ((q >> 1) & 3);
; #pragma unroll
;                 for (int bj = 0; bj < 2; ++bj)
; #pragma unroll
;                     for (int n = 0; n < 2; ++n) { const f32x4 v = acc[ai][bj][m][n] * rs;
;                         int w = __builtin_amdgcn_cvt_pk_fp8_f32(clamp448(v[0]), clamp448(v[1]), 0, false); w = __builtin_amdgcn_cvt_pk_fp8_f32(clamp448(v[2]), clamp448(v[3]), w, true);
;                         *(unsigned*)(VT + ((size_t)((2 * u.pn + bj) * 128 + dcol + 4 * n)) * NTOK + tpos) = (unsigned)w; } }
.LBB0_4165:
	s_lshl_b32 s4, s4, 8
	s_add_i32 s36, s4, s63
	v_or_b32_e32 v142, s36, v145
	v_ashrrev_i32_e32 v143, 31, v142
	v_lshlrev_b64 v[152:153], 6, v[142:143]
	v_or_b32_e32 v160, 1, v142
	v_lshl_add_u64 v[156:157], s[8:9], 0, v[152:153]
	v_ashrrev_i32_e32 v161, 31, v160
	global_load_dwordx4 v[152:155], v[156:157], off offset:32
	s_nop 0
	global_load_dwordx4 v[156:159], v[156:157], off offset:48
	v_lshlrev_b64 v[160:161], 6, v[160:161]
	v_lshl_add_u64 v[164:165], s[8:9], 0, v[160:161]
	global_load_dwordx4 v[160:163], v[164:165], off offset:32
	s_nop 0
	global_load_dwordx4 v[164:167], v[164:165], off offset:48
	v_cvt_f32_i32_e32 v115, v115
	v_cvt_f32_i32_e32 v114, v114
	v_cvt_f32_i32_e32 v113, v113
	v_cvt_f32_i32_e32 v112, v112
	v_cvt_f32_i32_e32 v169, v119
	v_cvt_f32_i32_e32 v168, v118
	v_cvt_f32_i32_e32 v117, v117
	v_cvt_f32_i32_e32 v116, v116
	v_cvt_f32_i32_e32 v127, v127
	v_cvt_f32_i32_e32 v126, v126
	v_cvt_f32_i32_e32 v125, v125
	v_cvt_f32_i32_e32 v124, v124
	v_cvt_f32_i32_e32 v123, v123
	v_cvt_f32_i32_e32 v122, v122
	v_cvt_f32_i32_e32 v121, v121
	v_cvt_f32_i32_e32 v120, v120
	v_or_b32_e32 v170, 2, v142
	v_or_b32_e32 v172, 3, v142
	v_ashrrev_i32_e32 v171, 31, v170
	v_ashrrev_i32_e32 v173, 31, v172
	v_pk_mul_f32 v[186:187], v[112:113], s[18:19] op_sel_hi:[1,0]
	v_pk_mul_f32 v[188:189], v[114:115], s[18:19] op_sel_hi:[1,0]
	v_lshlrev_b64 v[112:113], 6, v[170:171]
	v_lshlrev_b64 v[114:115], 6, v[172:173]
	v_pk_mul_f32 v[182:183], v[116:117], s[18:19] op_sel_hi:[1,0]
	v_pk_mul_f32 v[184:185], v[168:169], s[18:19] op_sel_hi:[1,0]
	v_lshl_add_u64 v[116:117], s[8:9], 0, v[112:113]
	v_lshl_add_u64 v[168:169], s[8:9], 0, v[114:115]
	v_pk_mul_f32 v[174:175], v[124:125], s[18:19] op_sel_hi:[1,0]
	v_pk_mul_f32 v[176:177], v[126:127], s[18:19] op_sel_hi:[1,0]
	v_pk_mul_f32 v[178:179], v[120:121], s[18:19] op_sel_hi:[1,0]
	v_pk_mul_f32 v[180:181], v[122:123], s[18:19] op_sel_hi:[1,0]
	global_load_dwordx4 v[112:115], v[116:117], off offset:32
	global_load_dwordx4 v[120:123], v[116:117], off offset:48
	global_load_dwordx4 v[124:127], v[168:169], off offset:32
	s_nop 0
	global_load_dwordx4 v[168:171], v[168:169], off offset:48
	v_lshl_or_b32 v118, s5, 8, v146
	s_ashr_i32 s37, s36, 31
	v_cvt_f32_i32_e32 v109, v109
	v_cvt_f32_i32_e32 v108, v108
	v_cvt_f32_i32_e32 v105, v105
	v_cvt_f32_i32_e32 v104, v104
	v_cvt_f32_i32_e32 v97, v97
	v_cvt_f32_i32_e32 v96, v96
	v_cvt_f32_i32_e32 v99, v99
	v_cvt_f32_i32_e32 v98, v98
	v_cvt_f32_i32_e32 v101, v101
	v_pk_mul_f32 v[172:173], v[96:97], s[18:19] op_sel_hi:[1,0]
	v_cvt_f32_i32_e32 v100, v100
	v_cvt_f32_i32_e32 v103, v103
	v_cvt_f32_i32_e32 v102, v102
	v_cvt_f32_i32_e32 v93, v93
	v_pk_mul_f32 v[100:101], v[100:101], s[18:19] op_sel_hi:[1,0]
	v_cvt_f32_i32_e32 v92, v92
	v_pk_mul_f32 v[102:103], v[102:103], s[18:19] op_sel_hi:[1,0]
	v_cvt_f32_i32_e32 v89, v89
	v_cvt_f32_i32_e32 v88, v88
	v_cvt_f32_i32_e32 v81, v81
	v_cvt_f32_i32_e32 v80, v80
	v_cvt_f32_i32_e32 v83, v83
	v_cvt_f32_i32_e32 v82, v82
	v_cvt_f32_i32_e32 v85, v85
	v_cvt_f32_i32_e32 v84, v84
	v_cvt_f32_i32_e32 v87, v87
	v_cvt_f32_i32_e32 v86, v86
	v_cvt_f32_i32_e32 v77, v77
	v_pk_mul_f32 v[84:85], v[84:85], s[18:19] op_sel_hi:[1,0]
	v_cvt_f32_i32_e32 v76, v76
	v_pk_mul_f32 v[86:87], v[86:87], s[18:19] op_sel_hi:[1,0]
	v_cvt_f32_i32_e32 v73, v73
	v_cvt_f32_i32_e32 v72, v72
	v_cvt_f32_i32_e32 v65, v65
	v_cvt_f32_i32_e32 v64, v64
	v_cvt_f32_i32_e32 v67, v67
	v_cvt_f32_i32_e32 v66, v66
	v_cvt_f32_i32_e32 v69, v69
	v_cvt_f32_i32_e32 v68, v68
	v_cvt_f32_i32_e32 v71, v71
	s_waitcnt vmcnt(0)
	v_mov_b32_e32 v116, v152
	v_mov_b32_e32 v117, v156
	v_mov_b32_e32 v156, v153
	v_mov_b32_e32 v152, v154
	v_mov_b32_e32 v153, v158
	v_mov_b32_e32 v158, v155
	v_pk_add_f32 v[116:117], v[116:117], v[156:157]
	v_pk_add_f32 v[152:153], v[152:153], v[158:159]
	v_mov_b32_e32 v154, v160
	v_mov_b32_e32 v155, v164
	v_mov_b32_e32 v164, v161
	v_mov_b32_e32 v156, v162
	v_mov_b32_e32 v157, v166
	v_mov_b32_e32 v166, v163
	v_pk_add_f32 v[116:117], v[116:117], v[152:153]
	v_pk_add_f32 v[152:153], v[154:155], v[164:165]
	v_pk_add_f32 v[154:155], v[156:157], v[166:167]
	v_add_f32_e32 v119, v116, v117
	v_pk_add_f32 v[116:117], v[152:153], v[154:155]
	v_fmamk_f32 v119, v119, 0x3b000000, v148
	v_rsq_f32_e32 v246, v119
	v_add_f32_e32 v116, v116, v117
	v_fmamk_f32 v116, v116, 0x3b000000, v148
	v_rsq_f32_e32 v247, v116
	v_or_b32_e32 v160, 17, v142
	v_ashrrev_i32_e32 v161, 31, v160
	v_lshlrev_b64 v[160:161], 6, v[160:161]
	v_mov_b32_e32 v152, v112
	v_mov_b32_e32 v153, v120
	v_mov_b32_e32 v120, v113
	v_pk_add_f32 v[112:113], v[152:153], v[120:121]
	v_mov_b32_e32 v120, v114
	v_mov_b32_e32 v121, v122
	v_mov_b32_e32 v122, v115
	v_pk_add_f32 v[114:115], v[120:121], v[122:123]
	v_pk_add_f32 v[112:113], v[112:113], v[114:115]
	v_add_f32_e32 v112, v112, v113
	v_fmamk_f32 v112, v112, 0x3b000000, v148
	v_rsq_f32_e32 v248, v112
	v_mov_b32_e32 v116, v246
	v_lshl_add_u64 v[164:165], s[8:9], 0, v[160:161]
	v_cvt_f32_i32_e32 v70, v70
	v_pk_mul_f32 v[68:69], v[68:69], s[18:19] op_sel_hi:[1,0]
	v_mov_b32_e32 v115, v170
	v_mov_b32_e32 v170, v127
	v_mov_b32_e32 v117, v247
	v_mov_b32_e32 v113, v168
	v_mov_b32_e32 v112, v124
	v_mov_b32_e32 v168, v125
	v_mov_b32_e32 v114, v126
	v_pk_add_f32 v[112:113], v[112:113], v[168:169]
	v_pk_add_f32 v[114:115], v[114:115], v[170:171]
	v_pk_add_f32 v[112:113], v[112:113], v[114:115]
	v_add_f32_e32 v112, v112, v113
	v_fmamk_f32 v112, v112, 0x3b000000, v148
	v_rsq_f32_e32 v249, v112
	v_pk_mul_f32 v[126:127], v[116:117], s[20:21] op_sel_hi:[1,0]
	v_lshl_add_u64 v[154:155], v[136:137], 0, s[36:37]
	v_pk_mul_f32 v[124:125], v[182:183], v[126:127]
	v_mov_b32_e32 v143, 0
; __device__ __forceinline__ float clamp448(float x) { return __builtin_amdgcn_fmed3f(x, -448.0f, 448.0f); }
; __device__ __forceinline__ float rms_scale(const float* ssq, int row, int which) {
;     const f32x4 a = *(const f32x4*)(ssq + (size_t)row * 16 + which * 8), b = *(const f32x4*)(ssq + (size_t)row * 16 + which * 8 + 4);
;     const float s = ((a[0] + a[1]) + (a[2] + a[3])) + ((b[0] + b[1]) + (b[2] + b[3]));
;     return 1.0f / sqrtf(s * (1.0f / 512.0f) + RMS_EPS);
;     __device__ __forceinline__ void operator()(EPI_ARGS) const {
;     ...
;             for (int m = 0; m < 4; ++m) { const int t0 = u.pm * BM + ai * HALF + wr * 64 + 16 * m + 4 * fq, q = 4 * m + fq;
;                 const f32x4 rs = (f32x4){rms_scale(ssq, t0, 1), rms_scale(ssq, t0 + 1, 1), rms_scale(ssq, t0 + 2, 1), rms_scale(ssq, t0 + 3, 1)} * osc;
;                 const size_t tpos = (size_t)(t0 & ~63) + 32 * (q & 1) + 16 * (q >> 3) + 4 * ((q >> 1) & 3);
; #pragma unroll
;                 for (int bj = 0; bj < 2; ++bj)
; #pragma unroll
;                     for (int n = 0; n < 2; ++n) { const f32x4 v = acc[ai][bj][m][n] * rs;
;                         int w = __builtin_amdgcn_cvt_pk_fp8_f32(clamp448(v[0]), clamp448(v[1]), 0, false); w = __builtin_amdgcn_cvt_pk_fp8_f32(clamp448(v[2]), clamp448(v[3]), w, true);
;                         *(unsigned*)(VT + ((size_t)((2 * u.pn + bj) * 128 + dcol + 4 * n)) * NTOK + tpos) = (unsigned)w; } }
	v_cvt_f32_i32_e32 v169, v111
	v_cvt_f32_i32_e32 v168, v110
	v_pk_mul_f32 v[110:111], v[108:109], s[18:19] op_sel_hi:[1,0]
	v_mov_b32_e32 v112, v248
	v_pk_mul_f32 v[108:109], v[168:169], s[18:19] op_sel_hi:[1,0]
	v_mov_b32_e32 v113, v249
	v_pk_mul_f32 v[152:153], v[112:113], s[20:21] op_sel_hi:[1,0]
	v_pk_mul_f32 v[112:113], v[174:175], v[126:127]
	v_med3_f32 v112, v112, s69, v150
	v_med3_f32 v113, v113, s69, v150
	v_cvt_pk_fp8_f32 v114, v112, v113
	v_pk_mul_f32 v[112:113], v[176:177], v[152:153]
	v_ashrrev_i32_e32 v119, 31, v118
	v_med3_f32 v112, v112, s69, v150
	v_med3_f32 v113, v113, s69, v150
	v_cvt_pk_fp8_f32 v114, v112, v113 op_sel:[0,0,1]
	v_lshlrev_b64 v[112:113], 14, v[118:119]
	v_lshl_add_u64 v[120:121], v[154:155], 0, v[112:113]
	global_store_dword v[120:121], v114, off
	v_pk_mul_f32 v[114:115], v[178:179], v[126:127]
	v_pk_mul_f32 v[126:127], v[186:187], v[126:127]
	v_med3_f32 v114, v114, s69, v150
	v_med3_f32 v115, v115, s69, v150
	v_cvt_pk_fp8_f32 v119, v114, v115
	v_pk_mul_f32 v[114:115], v[180:181], v[152:153]
	v_cvt_f32_i32_e32 v169, v107
	v_med3_f32 v114, v114, s69, v150
	v_med3_f32 v115, v115, s69, v150
	v_cvt_pk_fp8_f32 v119, v114, v115 op_sel:[0,0,1]
	v_or_b32_e32 v114, 4, v118
	v_ashrrev_i32_e32 v115, 31, v114
	v_lshlrev_b64 v[116:117], 14, v[114:115]
	v_lshl_add_u64 v[122:123], v[154:155], 0, v[116:117]
	global_store_dword v[122:123], v119, off
	v_med3_f32 v115, v124, s69, v150
	v_med3_f32 v119, v125, s69, v150
	v_cvt_pk_fp8_f32 v143, v115, v119
	v_pk_mul_f32 v[124:125], v[184:185], v[152:153]
	v_or_b32_e32 v114, 0x80, v118
	v_med3_f32 v115, v124, s69, v150
	v_med3_f32 v119, v125, s69, v150
	v_cvt_pk_fp8_f32 v143, v115, v119 op_sel:[0,0,1]
	v_ashrrev_i32_e32 v115, 31, v114
	v_lshlrev_b64 v[114:115], 14, v[114:115]
	v_lshl_add_u64 v[124:125], v[154:155], 0, v[114:115]
	global_store_dword v[124:125], v143, off
	v_med3_f32 v119, v126, s69, v150
	v_med3_f32 v126, v127, s69, v150
	v_cvt_pk_fp8_f32 v143, v119, v126
	v_pk_mul_f32 v[126:127], v[188:189], v[152:153]
	v_or_b32_e32 v118, 0x84, v118
	v_med3_f32 v119, v126, s69, v150
	v_med3_f32 v126, v127, s69, v150
	v_cvt_pk_fp8_f32 v143, v119, v126 op_sel:[0,0,1]
	v_ashrrev_i32_e32 v119, 31, v118
	v_or_b32_e32 v152, 16, v142
	v_lshlrev_b64 v[118:119], 14, v[118:119]
	v_ashrrev_i32_e32 v153, 31, v152
	v_lshl_add_u64 v[126:127], v[154:155], 0, v[118:119]
	v_lshlrev_b64 v[152:153], 6, v[152:153]
	global_store_dword v[126:127], v143, off
	v_lshl_add_u64 v[156:157], s[8:9], 0, v[152:153]
	global_load_dwordx4 v[152:155], v[156:157], off offset:32
	s_nop 0
	global_load_dwordx4 v[156:159], v[156:157], off offset:48
	s_nop 0
	global_load_dwordx4 v[160:163], v[164:165], off offset:32
	s_nop 0
	global_load_dwordx4 v[164:167], v[164:165], off offset:48
	v_cvt_f32_i32_e32 v168, v106
	v_pk_mul_f32 v[106:107], v[104:105], s[18:19] op_sel_hi:[1,0]
	v_pk_mul_f32 v[174:175], v[98:99], s[18:19] op_sel_hi:[1,0]
	v_pk_mul_f32 v[70:71], v[70:71], s[18:19] op_sel_hi:[1,0]
	v_pk_mul_f32 v[104:105], v[168:169], s[18:19] op_sel_hi:[1,0]
	s_addk_i32 s36, 0x80
	v_cvt_f32_i32_e32 v61, v61
	v_cvt_f32_i32_e32 v60, v60
	v_cvt_f32_i32_e32 v57, v57
	v_cvt_f32_i32_e32 v56, v56
	v_cvt_f32_i32_e32 v53, v53
	v_cvt_f32_i32_e32 v52, v52
	v_cvt_f32_i32_e32 v49, v49
	v_cvt_f32_i32_e32 v48, v48
	v_cvt_f32_i32_e32 v51, v51
	v_cvt_f32_i32_e32 v50, v50
	s_ashr_i32 s37, s36, 31
	v_cvt_f32_i32_e32 v45, v45
	v_cvt_f32_i32_e32 v44, v44
	v_cvt_f32_i32_e32 v41, v41
	v_cvt_f32_i32_e32 v40, v40
	v_cvt_f32_i32_e32 v33, v33
	v_cvt_f32_i32_e32 v32, v32
	v_cvt_f32_i32_e32 v35, v35
	v_cvt_f32_i32_e32 v34, v34
	v_cvt_f32_i32_e32 v37, v37
	v_cvt_f32_i32_e32 v36, v36
	v_cvt_f32_i32_e32 v39, v39
	v_cvt_f32_i32_e32 v38, v38
	v_cvt_f32_i32_e32 v29, v29
	v_pk_mul_f32 v[36:37], v[36:37], s[18:19] op_sel_hi:[1,0]
	v_cvt_f32_i32_e32 v28, v28
	v_pk_mul_f32 v[38:39], v[38:39], s[18:19] op_sel_hi:[1,0]
	v_cvt_f32_i32_e32 v25, v25
	v_cvt_f32_i32_e32 v24, v24
	v_cvt_f32_i32_e32 v17, v17
	v_cvt_f32_i32_e32 v16, v16
	v_cvt_f32_i32_e32 v19, v19
	v_cvt_f32_i32_e32 v18, v18
	v_cvt_f32_i32_e32 v21, v21
	v_cvt_f32_i32_e32 v20, v20
	v_cvt_f32_i32_e32 v23, v23
	v_cvt_f32_i32_e32 v22, v22
	v_cvt_f32_i32_e32 v13, v13
	v_pk_mul_f32 v[20:21], v[20:21], s[18:19] op_sel_hi:[1,0]
	v_cvt_f32_i32_e32 v12, v12
	v_pk_mul_f32 v[22:23], v[22:23], s[18:19] op_sel_hi:[1,0]
	v_cvt_f32_i32_e32 v9, v9
	v_cvt_f32_i32_e32 v8, v8
	v_cvt_f32_i32_e32 v1, v1
	v_cvt_f32_i32_e32 v0, v0
	v_cvt_f32_i32_e32 v3, v3
	v_cvt_f32_i32_e32 v2, v2
	v_cvt_f32_i32_e32 v5, v5
	v_cvt_f32_i32_e32 v4, v4
	v_cvt_f32_i32_e32 v7, v7
	v_cvt_f32_i32_e32 v6, v6
	v_pk_mul_f32 v[4:5], v[4:5], s[18:19] op_sel_hi:[1,0]
	v_pk_mul_f32 v[6:7], v[6:7], s[18:19] op_sel_hi:[1,0]
	s_waitcnt vmcnt(3)
	v_mov_b32_e32 v168, v152
	s_waitcnt vmcnt(2)
	v_mov_b32_e32 v169, v156
	v_mov_b32_e32 v156, v153
	v_pk_add_f32 v[152:153], v[168:169], v[156:157]
	v_mov_b32_e32 v156, v154
	v_mov_b32_e32 v157, v158
	v_mov_b32_e32 v158, v155
	v_pk_add_f32 v[154:155], v[156:157], v[158:159]
	s_waitcnt vmcnt(0)
	v_mov_b32_e32 v97, v164
	v_pk_add_f32 v[152:153], v[152:153], v[154:155]
	v_mov_b32_e32 v164, v161
	v_add_f32_e32 v143, v152, v153
	v_fmamk_f32 v143, v143, 0x3b000000, v148
	v_rsq_f32_e32 v250, v143
	v_or_b32_e32 v152, 18, v142
	v_ashrrev_i32_e32 v153, 31, v152
	v_lshlrev_b64 v[152:153], 6, v[152:153]
	v_lshl_add_u64 v[156:157], s[8:9], 0, v[152:153]
	global_load_dwordx4 v[152:155], v[156:157], off offset:32
	s_nop 0
	global_load_dwordx4 v[156:159], v[156:157], off offset:48
	s_nop 0
	s_nop 1
	s_nop 1
	v_mov_b32_e32 v96, v160
	v_pk_add_f32 v[160:161], v[96:97], v[164:165]
	v_or_b32_e32 v96, 19, v142
	v_ashrrev_i32_e32 v97, 31, v96
	v_lshlrev_b64 v[96:97], 6, v[96:97]
	v_lshl_add_u64 v[164:165], s[8:9], 0, v[96:97]
	global_load_dwordx4 v[96:99], v[164:165], off offset:32
	global_load_dwordx4 v[168:171], v[164:165], off offset:48
	v_mov_b32_e32 v164, v162
	v_mov_b32_e32 v165, v166
	v_mov_b32_e32 v166, v163
	v_pk_add_f32 v[162:163], v[164:165], v[166:167]
	v_pk_add_f32 v[160:161], v[160:161], v[162:163]
	v_add_f32_e32 v160, v160, v161
	v_fmamk_f32 v160, v160, 0x3b000000, v148
	v_rsq_f32_e32 v251, v160
	s_nop 0
	s_nop 1
	s_waitcnt vmcnt(3)
; __device__ __forceinline__ float clamp448(float x) { return __builtin_amdgcn_fmed3f(x, -448.0f, 448.0f); }
; __device__ __forceinline__ float rms_scale(const float* ssq, int row, int which) {
;     const f32x4 a = *(const f32x4*)(ssq + (size_t)row * 16 + which * 8), b = *(const f32x4*)(ssq + (size_t)row * 16 + which * 8 + 4);
;     const float s = ((a[0] + a[1]) + (a[2] + a[3])) + ((b[0] + b[1]) + (b[2] + b[3]));
;     return 1.0f / sqrtf(s * (1.0f / 512.0f) + RMS_EPS);
;     __device__ __forceinline__ void operator()(EPI_ARGS) const {
;     ...
;             for (int m = 0; m < 4; ++m) { const int t0 = u.pm * BM + ai * HALF + wr * 64 + 16 * m + 4 * fq, q = 4 * m + fq;
;                 const f32x4 rs = (f32x4){rms_scale(ssq, t0, 1), rms_scale(ssq, t0 + 1, 1), rms_scale(ssq, t0 + 2, 1), rms_scale(ssq, t0 + 3, 1)} * osc;
;                 const size_t tpos = (size_t)(t0 & ~63) + 32 * (q & 1) + 16 * (q >> 3) + 4 * ((q >> 1) & 3);
; #pragma unroll
;                 for (int bj = 0; bj < 2; ++bj)
; #pragma unroll
;                     for (int n = 0; n < 2; ++n) { const f32x4 v = acc[ai][bj][m][n] * rs;
;                         int w = __builtin_amdgcn_cvt_pk_fp8_f32(clamp448(v[0]), clamp448(v[1]), 0, false); w = __builtin_amdgcn_cvt_pk_fp8_f32(clamp448(v[2]), clamp448(v[3]), w, true);
;                         *(unsigned*)(VT + ((size_t)((2 * u.pn + bj) * 128 + dcol + 4 * n)) * NTOK + tpos) = (unsigned)w; } }
	v_mov_b32_e32 v162, v152
	s_waitcnt vmcnt(2)
	v_mov_b32_e32 v163, v156
	v_mov_b32_e32 v156, v153
	v_pk_add_f32 v[152:153], v[162:163], v[156:157]
	v_mov_b32_e32 v156, v154
	v_mov_b32_e32 v157, v158
	v_mov_b32_e32 v158, v155
	v_pk_add_f32 v[154:155], v[156:157], v[158:159]
	v_pk_add_f32 v[152:153], v[152:153], v[154:155]
	v_add_f32_e32 v152, v152, v153
	v_fmamk_f32 v152, v152, 0x3b000000, v148
	v_rsq_f32_e32 v252, v152
	v_mov_b32_e32 v160, v250
	v_mov_b32_e32 v161, v251
	v_pk_mul_f32 v[158:159], v[82:83], s[18:19] op_sel_hi:[1,0]
	s_nop 0
	s_waitcnt vmcnt(1)
	v_mov_b32_e32 v152, v96
	s_waitcnt vmcnt(0)
	v_mov_b32_e32 v153, v168
	v_mov_b32_e32 v168, v97
	v_pk_add_f32 v[96:97], v[152:153], v[168:169]
	v_mov_b32_e32 v152, v98
	v_mov_b32_e32 v153, v170
	v_mov_b32_e32 v170, v99
	v_pk_add_f32 v[98:99], v[152:153], v[170:171]
	v_pk_add_f32 v[96:97], v[96:97], v[98:99]
	v_add_f32_e32 v96, v96, v97
	v_fmamk_f32 v96, v96, 0x3b000000, v148
	v_rsq_f32_e32 v253, v96
	v_cvt_f32_i32_e32 v153, v95
	s_nop 1
	s_nop 1
	v_mov_b32_e32 v96, v252
	v_pk_mul_f32 v[156:157], v[80:81], s[18:19] op_sel_hi:[1,0]
	v_mov_b32_e32 v97, v253
	v_pk_mul_f32 v[98:99], v[160:161], s[20:21] op_sel_hi:[1,0]
	v_pk_mul_f32 v[110:111], v[110:111], v[98:99]
	v_pk_mul_f32 v[96:97], v[96:97], s[20:21] op_sel_hi:[1,0]
	v_med3_f32 v110, v110, s69, v150
	v_med3_f32 v111, v111, s69, v150
	v_cvt_pk_fp8_f32 v143, v110, v111
	v_pk_mul_f32 v[108:109], v[108:109], v[96:97]
	v_pk_mul_f32 v[106:107], v[106:107], v[98:99]
	v_med3_f32 v108, v108, s69, v150
	v_med3_f32 v109, v109, s69, v150
	v_cvt_pk_fp8_f32 v143, v108, v109 op_sel:[0,0,1]
	v_med3_f32 v106, v106, s69, v150
	v_med3_f32 v107, v107, s69, v150
	v_cvt_pk_fp8_f32 v108, v106, v107
	v_pk_mul_f32 v[104:105], v[104:105], v[96:97]
	v_pk_mul_f32 v[100:101], v[100:101], v[98:99]
	v_med3_f32 v104, v104, s69, v150
	v_med3_f32 v105, v105, s69, v150
	v_cvt_pk_fp8_f32 v108, v104, v105 op_sel:[0,0,1]
	v_med3_f32 v100, v100, s69, v150
	v_med3_f32 v101, v101, s69, v150
	v_cvt_pk_fp8_f32 v104, v100, v101
	v_pk_mul_f32 v[100:101], v[102:103], v[96:97]
	v_pk_mul_f32 v[98:99], v[172:173], v[98:99]
	v_med3_f32 v100, v100, s69, v150
	v_med3_f32 v101, v101, s69, v150
	v_cvt_pk_fp8_f32 v104, v100, v101 op_sel:[0,0,1]
	v_med3_f32 v98, v98, s69, v150
	v_med3_f32 v99, v99, s69, v150
	v_cvt_pk_fp8_f32 v100, v98, v99
	v_pk_mul_f32 v[96:97], v[174:175], v[96:97]
	v_cvt_f32_i32_e32 v152, v94
	v_med3_f32 v96, v96, s69, v150
	v_med3_f32 v97, v97, s69, v150
	v_cvt_pk_fp8_f32 v100, v96, v97 op_sel:[0,0,1]
	v_or_b32_e32 v96, 32, v142
	v_ashrrev_i32_e32 v97, 31, v96
	v_lshlrev_b64 v[96:97], 6, v[96:97]
	global_store_dword v[120:121], v143, off offset:8
	global_store_dword v[122:123], v108, off offset:8
	global_store_dword v[124:125], v104, off offset:8
	global_store_dword v[126:127], v100, off offset:8
	v_lshl_add_u64 v[100:101], s[8:9], 0, v[96:97]
	global_load_dwordx4 v[96:99], v[100:101], off offset:32
	s_nop 0
	global_load_dwordx4 v[100:103], v[100:101], off offset:48
	v_or_b32_e32 v104, 33, v142
	v_ashrrev_i32_e32 v105, 31, v104
	v_lshlrev_b64 v[104:105], 6, v[104:105]
	v_lshl_add_u64 v[108:109], s[8:9], 0, v[104:105]
	global_load_dwordx4 v[104:107], v[108:109], off offset:32
	s_nop 0
	global_load_dwordx4 v[108:111], v[108:109], off offset:48
	v_pk_mul_f32 v[94:95], v[92:93], s[18:19] op_sel_hi:[1,0]
	v_pk_mul_f32 v[92:93], v[152:153], s[18:19] op_sel_hi:[1,0]
	v_cvt_f32_i32_e32 v153, v91
	v_cvt_f32_i32_e32 v152, v90
	v_pk_mul_f32 v[90:91], v[88:89], s[18:19] op_sel_hi:[1,0]
	v_pk_mul_f32 v[88:89], v[152:153], s[18:19] op_sel_hi:[1,0]
	s_waitcnt vmcnt(3)
	v_mov_b32_e32 v152, v96
	s_waitcnt vmcnt(2)
	v_mov_b32_e32 v153, v100
	v_mov_b32_e32 v100, v97
	v_pk_add_f32 v[96:97], v[152:153], v[100:101]
	v_mov_b32_e32 v100, v98
	v_mov_b32_e32 v101, v102
	v_mov_b32_e32 v102, v99
	v_pk_add_f32 v[98:99], v[100:101], v[102:103]
	s_waitcnt vmcnt(0)
	v_mov_b32_e32 v81, v108
	v_pk_add_f32 v[96:97], v[96:97], v[98:99]
	v_mov_b32_e32 v108, v105
	v_add_f32_e32 v143, v96, v97
	v_or_b32_e32 v96, 34, v142
	v_ashrrev_i32_e32 v97, 31, v96
	v_lshlrev_b64 v[96:97], 6, v[96:97]
	v_lshl_add_u64 v[100:101], s[8:9], 0, v[96:97]
	global_load_dwordx4 v[96:99], v[100:101], off offset:32
	s_nop 0
	global_load_dwordx4 v[100:103], v[100:101], off offset:48
	v_fmamk_f32 v143, v143, 0x3b000000, v148
	v_rsq_f32_e32 v246, v143
	s_nop 1
	s_nop 0
	s_nop 0
	s_nop 1
	s_nop 1
	v_mov_b32_e32 v80, v104
	v_pk_add_f32 v[104:105], v[80:81], v[108:109]
	v_or_b32_e32 v80, 35, v142
	v_ashrrev_i32_e32 v81, 31, v80
	v_lshlrev_b64 v[80:81], 6, v[80:81]
	v_lshl_add_u64 v[108:109], s[8:9], 0, v[80:81]
	global_load_dwordx4 v[80:83], v[108:109], off offset:32
	global_load_dwordx4 v[152:155], v[108:109], off offset:48
	v_mov_b32_e32 v108, v106
	v_mov_b32_e32 v109, v110
	v_mov_b32_e32 v110, v107
	v_pk_add_f32 v[106:107], v[108:109], v[110:111]
	v_pk_add_f32 v[104:105], v[104:105], v[106:107]
	v_add_f32_e32 v104, v104, v105
	v_fmamk_f32 v104, v104, 0x3b000000, v148
	v_rsq_f32_e32 v247, v104
	s_nop 0
	s_nop 0
	s_nop 1
	s_waitcnt vmcnt(2)
	v_mov_b32_e32 v107, v100
	v_mov_b32_e32 v100, v97
	v_mov_b32_e32 v106, v96
	v_pk_add_f32 v[96:97], v[106:107], v[100:101]
	v_mov_b32_e32 v100, v98
	v_mov_b32_e32 v101, v102
	v_mov_b32_e32 v102, v99
	v_pk_add_f32 v[98:99], v[100:101], v[102:103]
	v_pk_add_f32 v[96:97], v[96:97], v[98:99]
	v_add_f32_e32 v96, v96, v97
	v_fmamk_f32 v96, v96, 0x3b000000, v148
	v_rsq_f32_e32 v248, v96
	v_mov_b32_e32 v104, v246
	s_nop 0
	s_nop 1
	s_nop 1
	v_mov_b32_e32 v105, v247
	s_waitcnt vmcnt(0)
; __device__ __forceinline__ float clamp448(float x) { return __builtin_amdgcn_fmed3f(x, -448.0f, 448.0f); }
; __device__ __forceinline__ float rms_scale(const float* ssq, int row, int which) {
;     const f32x4 a = *(const f32x4*)(ssq + (size_t)row * 16 + which * 8), b = *(const f32x4*)(ssq + (size_t)row * 16 + which * 8 + 4);
;     const float s = ((a[0] + a[1]) + (a[2] + a[3])) + ((b[0] + b[1]) + (b[2] + b[3]));
;     return 1.0f / sqrtf(s * (1.0f / 512.0f) + RMS_EPS);
;     __device__ __forceinline__ void operator()(EPI_ARGS) const {
;     ...
;             for (int m = 0; m < 4; ++m) { const int t0 = u.pm * BM + ai * HALF + wr * 64 + 16 * m + 4 * fq, q = 4 * m + fq;
;                 const f32x4 rs = (f32x4){rms_scale(ssq, t0, 1), rms_scale(ssq, t0 + 1, 1), rms_scale(ssq, t0 + 2, 1), rms_scale(ssq, t0 + 3, 1)} * osc;
;                 const size_t tpos = (size_t)(t0 & ~63) + 32 * (q & 1) + 16 * (q >> 3) + 4 * ((q >> 1) & 3);
; #pragma unroll
;                 for (int bj = 0; bj < 2; ++bj)
; #pragma unroll
;                     for (int n = 0; n < 2; ++n) { const f32x4 v = acc[ai][bj][m][n] * rs;
;                         int w = __builtin_amdgcn_cvt_pk_fp8_f32(clamp448(v[0]), clamp448(v[1]), 0, false); w = __builtin_amdgcn_cvt_pk_fp8_f32(clamp448(v[2]), clamp448(v[3]), w, true);
;                         *(unsigned*)(VT + ((size_t)((2 * u.pn + bj) * 128 + dcol + 4 * n)) * NTOK + tpos) = (unsigned)w; } }
	v_mov_b32_e32 v97, v152
	v_mov_b32_e32 v96, v80
	v_mov_b32_e32 v152, v81
	v_pk_add_f32 v[80:81], v[96:97], v[152:153]
	v_mov_b32_e32 v96, v82
	v_mov_b32_e32 v97, v154
	v_mov_b32_e32 v154, v83
	v_pk_add_f32 v[82:83], v[96:97], v[154:155]
	v_pk_add_f32 v[80:81], v[80:81], v[82:83]
	v_add_f32_e32 v80, v80, v81
	v_fmamk_f32 v80, v80, 0x3b000000, v148
	v_rsq_f32_e32 v249, v80
	s_nop 0
	s_nop 1
	s_nop 1
	v_mov_b32_e32 v80, v248
	v_pk_mul_f32 v[100:101], v[64:65], s[18:19] op_sel_hi:[1,0]
	v_mov_b32_e32 v81, v249
	v_pk_mul_f32 v[82:83], v[104:105], s[20:21] op_sel_hi:[1,0]
	v_pk_mul_f32 v[94:95], v[94:95], v[82:83]
	v_pk_mul_f32 v[80:81], v[80:81], s[20:21] op_sel_hi:[1,0]
	v_med3_f32 v94, v94, s69, v150
	v_med3_f32 v95, v95, s69, v150
	v_cvt_pk_fp8_f32 v96, v94, v95
	v_pk_mul_f32 v[92:93], v[92:93], v[80:81]
	v_pk_mul_f32 v[90:91], v[90:91], v[82:83]
	v_med3_f32 v92, v92, s69, v150
	v_med3_f32 v93, v93, s69, v150
	v_cvt_pk_fp8_f32 v96, v92, v93 op_sel:[0,0,1]
	v_med3_f32 v90, v90, s69, v150
	v_med3_f32 v91, v91, s69, v150
	v_cvt_pk_fp8_f32 v92, v90, v91
	v_pk_mul_f32 v[88:89], v[88:89], v[80:81]
	v_pk_mul_f32 v[84:85], v[84:85], v[82:83]
	v_med3_f32 v88, v88, s69, v150
	v_med3_f32 v89, v89, s69, v150
	v_cvt_pk_fp8_f32 v92, v88, v89 op_sel:[0,0,1]
	v_med3_f32 v84, v84, s69, v150
	v_med3_f32 v85, v85, s69, v150
	v_cvt_pk_fp8_f32 v88, v84, v85
	v_pk_mul_f32 v[84:85], v[86:87], v[80:81]
	v_pk_mul_f32 v[82:83], v[156:157], v[82:83]
	v_med3_f32 v84, v84, s69, v150
	v_med3_f32 v85, v85, s69, v150
	v_cvt_pk_fp8_f32 v88, v84, v85 op_sel:[0,0,1]
	v_med3_f32 v82, v82, s69, v150
	v_med3_f32 v83, v83, s69, v150
	v_cvt_pk_fp8_f32 v84, v82, v83
	v_pk_mul_f32 v[80:81], v[158:159], v[80:81]
	v_cvt_f32_i32_e32 v97, v79
	v_med3_f32 v80, v80, s69, v150
	v_med3_f32 v81, v81, s69, v150
	v_cvt_pk_fp8_f32 v84, v80, v81 op_sel:[0,0,1]
	v_or_b32_e32 v80, 48, v142
	v_ashrrev_i32_e32 v81, 31, v80
	v_lshlrev_b64 v[80:81], 6, v[80:81]
	global_store_dword v[120:121], v96, off offset:16
	global_store_dword v[122:123], v92, off offset:16
	global_store_dword v[124:125], v88, off offset:16
	global_store_dword v[126:127], v84, off offset:16
	v_lshl_add_u64 v[84:85], s[8:9], 0, v[80:81]
	global_load_dwordx4 v[80:83], v[84:85], off offset:32
	s_nop 0
	global_load_dwordx4 v[84:87], v[84:85], off offset:48
	v_or_b32_e32 v88, 49, v142
	v_ashrrev_i32_e32 v89, 31, v88
	v_lshlrev_b64 v[88:89], 6, v[88:89]
	v_lshl_add_u64 v[92:93], s[8:9], 0, v[88:89]
	global_load_dwordx4 v[88:91], v[92:93], off offset:32
	s_nop 0
	global_load_dwordx4 v[92:95], v[92:93], off offset:48
	v_cvt_f32_i32_e32 v96, v78
	v_pk_mul_f32 v[78:79], v[76:77], s[18:19] op_sel_hi:[1,0]
	v_pk_mul_f32 v[102:103], v[66:67], s[18:19] op_sel_hi:[1,0]
	v_pk_mul_f32 v[76:77], v[96:97], s[18:19] op_sel_hi:[1,0]
	v_cvt_f32_i32_e32 v97, v75
	v_cvt_f32_i32_e32 v96, v74
	v_pk_mul_f32 v[74:75], v[72:73], s[18:19] op_sel_hi:[1,0]
	v_pk_mul_f32 v[72:73], v[96:97], s[18:19] op_sel_hi:[1,0]
	s_waitcnt vmcnt(3)
	v_mov_b32_e32 v96, v80
	s_waitcnt vmcnt(2)
	v_mov_b32_e32 v97, v84
	v_mov_b32_e32 v84, v81
	v_pk_add_f32 v[80:81], v[96:97], v[84:85]
	v_mov_b32_e32 v84, v82
	v_mov_b32_e32 v85, v86
	v_mov_b32_e32 v86, v83
	v_pk_add_f32 v[82:83], v[84:85], v[86:87]
	s_waitcnt vmcnt(0)
	v_mov_b32_e32 v65, v92
	v_pk_add_f32 v[80:81], v[80:81], v[82:83]
	v_mov_b32_e32 v92, v89
	v_add_f32_e32 v96, v80, v81
	v_or_b32_e32 v80, 50, v142
	v_ashrrev_i32_e32 v81, 31, v80
	v_lshlrev_b64 v[80:81], 6, v[80:81]
	v_lshl_add_u64 v[84:85], s[8:9], 0, v[80:81]
	global_load_dwordx4 v[80:83], v[84:85], off offset:32
	s_nop 0
	global_load_dwordx4 v[84:87], v[84:85], off offset:48
	v_fmamk_f32 v96, v96, 0x3b000000, v148
	v_rsq_f32_e32 v250, v96
	s_nop 1
	s_nop 0
	s_nop 0
	s_nop 1
	s_nop 1
	v_mov_b32_e32 v64, v88
	v_pk_add_f32 v[88:89], v[64:65], v[92:93]
	v_or_b32_e32 v64, 51, v142
	v_ashrrev_i32_e32 v65, 31, v64
	v_lshlrev_b64 v[64:65], 6, v[64:65]
	v_lshl_add_u64 v[92:93], s[8:9], 0, v[64:65]
	global_load_dwordx4 v[64:67], v[92:93], off offset:32
	global_load_dwordx4 v[96:99], v[92:93], off offset:48
	v_mov_b32_e32 v92, v90
	v_mov_b32_e32 v93, v94
	v_mov_b32_e32 v94, v91
	v_pk_add_f32 v[90:91], v[92:93], v[94:95]
	v_pk_add_f32 v[88:89], v[88:89], v[90:91]
	v_add_f32_e32 v88, v88, v89
	v_fmamk_f32 v88, v88, 0x3b000000, v148
	v_rsq_f32_e32 v251, v88
	s_nop 0
	s_nop 0
	s_nop 1
	s_waitcnt vmcnt(2)
	v_mov_b32_e32 v91, v84
	v_mov_b32_e32 v84, v81
	v_mov_b32_e32 v90, v80
	v_pk_add_f32 v[80:81], v[90:91], v[84:85]
	v_mov_b32_e32 v84, v82
	v_mov_b32_e32 v85, v86
	v_mov_b32_e32 v86, v83
	v_pk_add_f32 v[82:83], v[84:85], v[86:87]
	v_pk_add_f32 v[80:81], v[80:81], v[82:83]
	v_add_f32_e32 v80, v80, v81
	v_fmamk_f32 v80, v80, 0x3b000000, v148
	v_rsq_f32_e32 v252, v80
	v_mov_b32_e32 v88, v250
	s_nop 0
	s_nop 1
	s_nop 1
	v_mov_b32_e32 v89, v251
	s_waitcnt vmcnt(0)
; __device__ __forceinline__ float clamp448(float x) { return __builtin_amdgcn_fmed3f(x, -448.0f, 448.0f); }
; __device__ __forceinline__ float rms_scale(const float* ssq, int row, int which) {
;     const f32x4 a = *(const f32x4*)(ssq + (size_t)row * 16 + which * 8), b = *(const f32x4*)(ssq + (size_t)row * 16 + which * 8 + 4);
;     const float s = ((a[0] + a[1]) + (a[2] + a[3])) + ((b[0] + b[1]) + (b[2] + b[3]));
;     return 1.0f / sqrtf(s * (1.0f / 512.0f) + RMS_EPS);
;     __device__ __forceinline__ void operator()(EPI_ARGS) const {
;     ...
;             for (int m = 0; m < 4; ++m) { const int t0 = u.pm * BM + ai * HALF + wr * 64 + 16 * m + 4 * fq, q = 4 * m + fq;
;                 const f32x4 rs = (f32x4){rms_scale(ssq, t0, 1), rms_scale(ssq, t0 + 1, 1), rms_scale(ssq, t0 + 2, 1), rms_scale(ssq, t0 + 3, 1)} * osc;
;                 const size_t tpos = (size_t)(t0 & ~63) + 32 * (q & 1) + 16 * (q >> 3) + 4 * ((q >> 1) & 3);
; #pragma unroll
;                 for (int bj = 0; bj < 2; ++bj)
; #pragma unroll
;                     for (int n = 0; n < 2; ++n) { const f32x4 v = acc[ai][bj][m][n] * rs;
;                         int w = __builtin_amdgcn_cvt_pk_fp8_f32(clamp448(v[0]), clamp448(v[1]), 0, false); w = __builtin_amdgcn_cvt_pk_fp8_f32(clamp448(v[2]), clamp448(v[3]), w, true);
;                         *(unsigned*)(VT + ((size_t)((2 * u.pn + bj) * 128 + dcol + 4 * n)) * NTOK + tpos) = (unsigned)w; } }
	v_mov_b32_e32 v81, v96
	v_mov_b32_e32 v80, v64
	v_mov_b32_e32 v96, v65
	v_pk_add_f32 v[64:65], v[80:81], v[96:97]
	v_mov_b32_e32 v80, v66
	v_mov_b32_e32 v81, v98
	v_mov_b32_e32 v98, v67
	v_pk_add_f32 v[66:67], v[80:81], v[98:99]
	v_pk_add_f32 v[64:65], v[64:65], v[66:67]
	v_add_f32_e32 v64, v64, v65
	v_fmamk_f32 v64, v64, 0x3b000000, v148
	v_rsq_f32_e32 v253, v64
	v_cvt_f32_i32_e32 v84, v54
	s_nop 0
	s_nop 1
	s_nop 1
	v_mov_b32_e32 v64, v252
	v_cvt_f32_i32_e32 v83, v63
	v_mov_b32_e32 v65, v253
	v_pk_mul_f32 v[66:67], v[88:89], s[20:21] op_sel_hi:[1,0]
	v_pk_mul_f32 v[78:79], v[78:79], v[66:67]
	v_pk_mul_f32 v[64:65], v[64:65], s[20:21] op_sel_hi:[1,0]
	v_med3_f32 v78, v78, s69, v150
	v_med3_f32 v79, v79, s69, v150
	v_cvt_pk_fp8_f32 v80, v78, v79
	v_pk_mul_f32 v[76:77], v[76:77], v[64:65]
	v_pk_mul_f32 v[74:75], v[74:75], v[66:67]
	v_med3_f32 v76, v76, s69, v150
	v_med3_f32 v77, v77, s69, v150
	v_cvt_pk_fp8_f32 v80, v76, v77 op_sel:[0,0,1]
	v_med3_f32 v74, v74, s69, v150
	v_med3_f32 v75, v75, s69, v150
	v_cvt_pk_fp8_f32 v76, v74, v75
	v_pk_mul_f32 v[72:73], v[72:73], v[64:65]
	v_pk_mul_f32 v[68:69], v[68:69], v[66:67]
	v_med3_f32 v72, v72, s69, v150
	v_med3_f32 v73, v73, s69, v150
	v_cvt_pk_fp8_f32 v76, v72, v73 op_sel:[0,0,1]
	v_med3_f32 v68, v68, s69, v150
	v_med3_f32 v69, v69, s69, v150
	v_cvt_pk_fp8_f32 v72, v68, v69
	v_pk_mul_f32 v[68:69], v[70:71], v[64:65]
	v_pk_mul_f32 v[66:67], v[100:101], v[66:67]
	v_med3_f32 v68, v68, s69, v150
	v_med3_f32 v69, v69, s69, v150
	v_cvt_pk_fp8_f32 v72, v68, v69 op_sel:[0,0,1]
	v_med3_f32 v66, v66, s69, v150
	v_med3_f32 v67, v67, s69, v150
	v_cvt_pk_fp8_f32 v68, v66, v67
	v_pk_mul_f32 v[64:65], v[102:103], v[64:65]
	v_cvt_f32_i32_e32 v82, v62
	v_med3_f32 v64, v64, s69, v150
	v_med3_f32 v65, v65, s69, v150
	v_cvt_pk_fp8_f32 v68, v64, v65 op_sel:[0,0,1]
	v_or_b32_e32 v64, s36, v145
	v_ashrrev_i32_e32 v65, 31, v64
	v_lshlrev_b64 v[66:67], 6, v[64:65]
	global_store_dword v[120:121], v80, off offset:24
	global_store_dword v[122:123], v76, off offset:24
	global_store_dword v[124:125], v72, off offset:24
	global_store_dword v[126:127], v68, off offset:24
	v_lshl_add_u64 v[70:71], s[8:9], 0, v[66:67]
	global_load_dwordx4 v[66:69], v[70:71], off offset:32
	s_nop 0
	global_load_dwordx4 v[70:73], v[70:71], off offset:48
	v_or_b32_e32 v74, 1, v64
	v_ashrrev_i32_e32 v75, 31, v74
	v_lshlrev_b64 v[74:75], 6, v[74:75]
	v_lshl_add_u64 v[78:79], s[8:9], 0, v[74:75]
	global_load_dwordx4 v[74:77], v[78:79], off offset:32
	s_nop 0
	global_load_dwordx4 v[78:81], v[78:79], off offset:48
	v_pk_mul_f32 v[62:63], v[60:61], s[18:19] op_sel_hi:[1,0]
	v_pk_mul_f32 v[60:61], v[82:83], s[18:19] op_sel_hi:[1,0]
	v_cvt_f32_i32_e32 v83, v59
	v_cvt_f32_i32_e32 v82, v58
	v_pk_mul_f32 v[58:59], v[56:57], s[18:19] op_sel_hi:[1,0]
	v_cvt_f32_i32_e32 v85, v55
	v_pk_mul_f32 v[54:55], v[52:53], s[18:19] op_sel_hi:[1,0]
	v_pk_mul_f32 v[56:57], v[82:83], s[18:19] op_sel_hi:[1,0]
	v_pk_mul_f32 v[86:87], v[48:49], s[18:19] op_sel_hi:[1,0]
	v_pk_mul_f32 v[52:53], v[84:85], s[18:19] op_sel_hi:[1,0]
	v_pk_mul_f32 v[88:89], v[50:51], s[18:19] op_sel_hi:[1,0]
	s_waitcnt vmcnt(3)
	v_mov_b32_e32 v82, v66
	s_waitcnt vmcnt(2)
	v_mov_b32_e32 v83, v70
	v_mov_b32_e32 v70, v67
	v_pk_add_f32 v[66:67], v[82:83], v[70:71]
	v_mov_b32_e32 v70, v68
	v_mov_b32_e32 v71, v72
	v_mov_b32_e32 v72, v69
	v_pk_add_f32 v[68:69], v[70:71], v[72:73]
	s_waitcnt vmcnt(0)
	v_mov_b32_e32 v49, v78
	v_pk_add_f32 v[66:67], v[66:67], v[68:69]
	v_mov_b32_e32 v78, v75
	v_add_f32_e32 v65, v66, v67
	v_fmamk_f32 v65, v65, 0x3b000000, v148
	v_rsq_f32_e32 v246, v65
	v_or_b32_e32 v66, 2, v64
	v_ashrrev_i32_e32 v67, 31, v66
	v_lshlrev_b64 v[66:67], 6, v[66:67]
	v_lshl_add_u64 v[70:71], s[8:9], 0, v[66:67]
	global_load_dwordx4 v[66:69], v[70:71], off offset:32
	s_nop 0
	global_load_dwordx4 v[70:73], v[70:71], off offset:48
	s_nop 0
	s_nop 1
	s_nop 1
	v_mov_b32_e32 v48, v74
	v_pk_add_f32 v[74:75], v[48:49], v[78:79]
	v_or_b32_e32 v48, 3, v64
	v_ashrrev_i32_e32 v49, 31, v48
	v_lshlrev_b64 v[48:49], 6, v[48:49]
	v_lshl_add_u64 v[78:79], s[8:9], 0, v[48:49]
	global_load_dwordx4 v[48:51], v[78:79], off offset:32
	global_load_dwordx4 v[82:85], v[78:79], off offset:48
	v_mov_b32_e32 v78, v76
	v_mov_b32_e32 v79, v80
	v_mov_b32_e32 v80, v77
	v_pk_add_f32 v[76:77], v[78:79], v[80:81]
	v_pk_add_f32 v[74:75], v[74:75], v[76:77]
	v_add_f32_e32 v74, v74, v75
	v_fmamk_f32 v74, v74, 0x3b000000, v148
	v_rsq_f32_e32 v247, v74
	s_nop 0
	s_nop 0
	s_nop 1
	s_waitcnt vmcnt(2)
	v_mov_b32_e32 v77, v70
	v_mov_b32_e32 v76, v66
	v_mov_b32_e32 v70, v67
	v_pk_add_f32 v[66:67], v[76:77], v[70:71]
	v_mov_b32_e32 v70, v68
	v_mov_b32_e32 v71, v72
	v_mov_b32_e32 v72, v69
	v_pk_add_f32 v[68:69], v[70:71], v[72:73]
	v_pk_add_f32 v[66:67], v[66:67], v[68:69]
	v_add_f32_e32 v66, v66, v67
	v_fmamk_f32 v66, v66, 0x3b000000, v148
	v_rsq_f32_e32 v248, v66
	v_mov_b32_e32 v74, v246
	v_mov_b32_e32 v75, v247
	v_pk_mul_f32 v[78:79], v[32:33], s[18:19] op_sel_hi:[1,0]
	v_pk_mul_f32 v[80:81], v[34:35], s[18:19] op_sel_hi:[1,0]
	s_waitcnt vmcnt(1)
	v_mov_b32_e32 v66, v48
	s_waitcnt vmcnt(0)
; __device__ __forceinline__ float clamp448(float x) { return __builtin_amdgcn_fmed3f(x, -448.0f, 448.0f); }
; __device__ __forceinline__ float rms_scale(const float* ssq, int row, int which) {
;     const f32x4 a = *(const f32x4*)(ssq + (size_t)row * 16 + which * 8), b = *(const f32x4*)(ssq + (size_t)row * 16 + which * 8 + 4);
;     const float s = ((a[0] + a[1]) + (a[2] + a[3])) + ((b[0] + b[1]) + (b[2] + b[3]));
;     return 1.0f / sqrtf(s * (1.0f / 512.0f) + RMS_EPS);
;     __device__ __forceinline__ void operator()(EPI_ARGS) const {
;     ...
;             for (int m = 0; m < 4; ++m) { const int t0 = u.pm * BM + ai * HALF + wr * 64 + 16 * m + 4 * fq, q = 4 * m + fq;
;                 const f32x4 rs = (f32x4){rms_scale(ssq, t0, 1), rms_scale(ssq, t0 + 1, 1), rms_scale(ssq, t0 + 2, 1), rms_scale(ssq, t0 + 3, 1)} * osc;
;                 const size_t tpos = (size_t)(t0 & ~63) + 32 * (q & 1) + 16 * (q >> 3) + 4 * ((q >> 1) & 3);
; #pragma unroll
;                 for (int bj = 0; bj < 2; ++bj)
; #pragma unroll
;                     for (int n = 0; n < 2; ++n) { const f32x4 v = acc[ai][bj][m][n] * rs;
;                         int w = __builtin_amdgcn_cvt_pk_fp8_f32(clamp448(v[0]), clamp448(v[1]), 0, false); w = __builtin_amdgcn_cvt_pk_fp8_f32(clamp448(v[2]), clamp448(v[3]), w, true);
;                         *(unsigned*)(VT + ((size_t)((2 * u.pn + bj) * 128 + dcol + 4 * n)) * NTOK + tpos) = (unsigned)w; } }
	v_mov_b32_e32 v67, v82
	v_mov_b32_e32 v82, v49
	v_pk_add_f32 v[48:49], v[66:67], v[82:83]
	v_mov_b32_e32 v66, v50
	v_mov_b32_e32 v67, v84
	v_mov_b32_e32 v84, v51
	v_pk_add_f32 v[50:51], v[66:67], v[84:85]
	v_pk_add_f32 v[48:49], v[48:49], v[50:51]
	v_add_f32_e32 v48, v48, v49
	v_fmamk_f32 v48, v48, 0x3b000000, v148
	v_rsq_f32_e32 v249, v48
	s_nop 0
	s_nop 1
	s_nop 1
	v_mov_b32_e32 v48, v248
	v_lshl_add_u64 v[70:71], v[136:137], 0, s[36:37]
	v_mov_b32_e32 v49, v249
	v_pk_mul_f32 v[66:67], v[74:75], s[20:21] op_sel_hi:[1,0]
	v_pk_mul_f32 v[68:69], v[48:49], s[20:21] op_sel_hi:[1,0]
	v_pk_mul_f32 v[48:49], v[62:63], v[66:67]
	v_med3_f32 v48, v48, s69, v150
	v_med3_f32 v49, v49, s69, v150
	v_cvt_pk_fp8_f32 v50, v48, v49
	v_pk_mul_f32 v[48:49], v[60:61], v[68:69]
	v_pk_mul_f32 v[54:55], v[54:55], v[66:67]
	v_med3_f32 v48, v48, s69, v150
	v_med3_f32 v49, v49, s69, v150
	v_cvt_pk_fp8_f32 v50, v48, v49 op_sel:[0,0,1]
	v_pk_mul_f32 v[48:49], v[58:59], v[66:67]
	v_med3_f32 v48, v48, s69, v150
	v_med3_f32 v49, v49, s69, v150
	v_cvt_pk_fp8_f32 v58, v48, v49
	v_pk_mul_f32 v[48:49], v[56:57], v[68:69]
	v_med3_f32 v54, v54, s69, v150
	v_med3_f32 v55, v55, s69, v150
	v_cvt_pk_fp8_f32 v56, v54, v55
	v_pk_mul_f32 v[52:53], v[52:53], v[68:69]
	v_med3_f32 v52, v52, s69, v150
	v_med3_f32 v53, v53, s69, v150
	v_cvt_pk_fp8_f32 v56, v52, v53 op_sel:[0,0,1]
	v_pk_mul_f32 v[52:53], v[86:87], v[66:67]
	v_med3_f32 v48, v48, s69, v150
	v_med3_f32 v52, v52, s69, v150
	v_med3_f32 v53, v53, s69, v150
	v_cvt_pk_fp8_f32 v57, v52, v53
	v_pk_mul_f32 v[52:53], v[88:89], v[68:69]
	v_med3_f32 v49, v49, s69, v150
	v_med3_f32 v52, v52, s69, v150
	v_med3_f32 v53, v53, s69, v150
	v_cvt_pk_fp8_f32 v57, v52, v53 op_sel:[0,0,1]
	v_cvt_pk_fp8_f32 v58, v48, v49 op_sel:[0,0,1]
	v_lshl_add_u64 v[52:53], v[70:71], 0, v[114:115]
	global_store_dword v[52:53], v56, off
	v_lshl_add_u64 v[54:55], v[70:71], 0, v[118:119]
	v_or_b32_e32 v56, 16, v64
	v_lshl_add_u64 v[48:49], v[70:71], 0, v[112:113]
	global_store_dword v[54:55], v57, off
	v_ashrrev_i32_e32 v57, 31, v56
	global_store_dword v[48:49], v50, off
	v_lshl_add_u64 v[50:51], v[70:71], 0, v[116:117]
	v_lshlrev_b64 v[56:57], 6, v[56:57]
	global_store_dword v[50:51], v58, off
	v_lshl_add_u64 v[60:61], s[8:9], 0, v[56:57]
	global_load_dwordx4 v[56:59], v[60:61], off offset:32
	s_nop 0
	global_load_dwordx4 v[60:63], v[60:61], off offset:48
	v_or_b32_e32 v66, 17, v64
	v_ashrrev_i32_e32 v67, 31, v66
	v_lshlrev_b64 v[66:67], 6, v[66:67]
	v_lshl_add_u64 v[70:71], s[8:9], 0, v[66:67]
	global_load_dwordx4 v[66:69], v[70:71], off offset:32
	s_nop 0
	global_load_dwordx4 v[70:73], v[70:71], off offset:48
	v_cvt_f32_i32_e32 v75, v47
	v_cvt_f32_i32_e32 v74, v46
	v_pk_mul_f32 v[46:47], v[44:45], s[18:19] op_sel_hi:[1,0]
	v_pk_mul_f32 v[44:45], v[74:75], s[18:19] op_sel_hi:[1,0]
	v_cvt_f32_i32_e32 v75, v43
	v_cvt_f32_i32_e32 v74, v42
	v_pk_mul_f32 v[42:43], v[40:41], s[18:19] op_sel_hi:[1,0]
	v_pk_mul_f32 v[40:41], v[74:75], s[18:19] op_sel_hi:[1,0]
	s_waitcnt vmcnt(3)
	v_mov_b32_e32 v74, v56
	s_waitcnt vmcnt(2)
	v_mov_b32_e32 v75, v60
	v_mov_b32_e32 v60, v57
	v_pk_add_f32 v[56:57], v[74:75], v[60:61]
	v_mov_b32_e32 v60, v58
	v_mov_b32_e32 v61, v62
	v_mov_b32_e32 v62, v59
	v_pk_add_f32 v[58:59], v[60:61], v[62:63]
	s_waitcnt vmcnt(0)
	v_mov_b32_e32 v33, v70
	v_pk_add_f32 v[56:57], v[56:57], v[58:59]
	v_mov_b32_e32 v70, v67
	v_add_f32_e32 v65, v56, v57
	v_or_b32_e32 v56, 18, v64
	v_ashrrev_i32_e32 v57, 31, v56
	v_lshlrev_b64 v[56:57], 6, v[56:57]
	v_lshl_add_u64 v[60:61], s[8:9], 0, v[56:57]
	global_load_dwordx4 v[56:59], v[60:61], off offset:32
	s_nop 0
	global_load_dwordx4 v[60:63], v[60:61], off offset:48
	v_fmamk_f32 v65, v65, 0x3b000000, v148
	v_rsq_f32_e32 v250, v65
	s_nop 1
	s_nop 0
	s_nop 0
	s_nop 1
	s_nop 1
	v_mov_b32_e32 v32, v66
	v_pk_add_f32 v[66:67], v[32:33], v[70:71]
	v_or_b32_e32 v32, 19, v64
	v_ashrrev_i32_e32 v33, 31, v32
	v_lshlrev_b64 v[32:33], 6, v[32:33]
	v_lshl_add_u64 v[70:71], s[8:9], 0, v[32:33]
	global_load_dwordx4 v[32:35], v[70:71], off offset:32
	global_load_dwordx4 v[74:77], v[70:71], off offset:48
	v_mov_b32_e32 v70, v68
	v_mov_b32_e32 v71, v72
	v_mov_b32_e32 v72, v69
	v_pk_add_f32 v[68:69], v[70:71], v[72:73]
	v_pk_add_f32 v[66:67], v[66:67], v[68:69]
	v_add_f32_e32 v66, v66, v67
	v_fmamk_f32 v66, v66, 0x3b000000, v148
	v_rsq_f32_e32 v251, v66
	s_nop 0
	s_nop 0
	s_nop 1
	s_waitcnt vmcnt(2)
	v_mov_b32_e32 v69, v60
	v_mov_b32_e32 v68, v56
	v_mov_b32_e32 v60, v57
	v_pk_add_f32 v[56:57], v[68:69], v[60:61]
	v_mov_b32_e32 v60, v58
	v_mov_b32_e32 v61, v62
	v_mov_b32_e32 v62, v59
	v_pk_add_f32 v[58:59], v[60:61], v[62:63]
	v_pk_add_f32 v[56:57], v[56:57], v[58:59]
	v_add_f32_e32 v56, v56, v57
	v_fmamk_f32 v56, v56, 0x3b000000, v148
	v_rsq_f32_e32 v252, v56
	v_mov_b32_e32 v66, v250
	s_nop 0
	v_mov_b32_e32 v67, v251
	s_waitcnt vmcnt(0)
; __device__ __forceinline__ float clamp448(float x) { return __builtin_amdgcn_fmed3f(x, -448.0f, 448.0f); }
; __device__ __forceinline__ float rms_scale(const float* ssq, int row, int which) {
;     const f32x4 a = *(const f32x4*)(ssq + (size_t)row * 16 + which * 8), b = *(const f32x4*)(ssq + (size_t)row * 16 + which * 8 + 4);
;     const float s = ((a[0] + a[1]) + (a[2] + a[3])) + ((b[0] + b[1]) + (b[2] + b[3]));
;     return 1.0f / sqrtf(s * (1.0f / 512.0f) + RMS_EPS);
;     __device__ __forceinline__ void operator()(EPI_ARGS) const {
;     ...
;             for (int m = 0; m < 4; ++m) { const int t0 = u.pm * BM + ai * HALF + wr * 64 + 16 * m + 4 * fq, q = 4 * m + fq;
;                 const f32x4 rs = (f32x4){rms_scale(ssq, t0, 1), rms_scale(ssq, t0 + 1, 1), rms_scale(ssq, t0 + 2, 1), rms_scale(ssq, t0 + 3, 1)} * osc;
;                 const size_t tpos = (size_t)(t0 & ~63) + 32 * (q & 1) + 16 * (q >> 3) + 4 * ((q >> 1) & 3);
; #pragma unroll
;                 for (int bj = 0; bj < 2; ++bj)
; #pragma unroll
;                     for (int n = 0; n < 2; ++n) { const f32x4 v = acc[ai][bj][m][n] * rs;
;                         int w = __builtin_amdgcn_cvt_pk_fp8_f32(clamp448(v[0]), clamp448(v[1]), 0, false); w = __builtin_amdgcn_cvt_pk_fp8_f32(clamp448(v[2]), clamp448(v[3]), w, true);
;                         *(unsigned*)(VT + ((size_t)((2 * u.pn + bj) * 128 + dcol + 4 * n)) * NTOK + tpos) = (unsigned)w; } }
	v_mov_b32_e32 v57, v74
	v_mov_b32_e32 v56, v32
	v_mov_b32_e32 v74, v33
	v_pk_add_f32 v[32:33], v[56:57], v[74:75]
	v_mov_b32_e32 v56, v34
	v_mov_b32_e32 v57, v76
	v_mov_b32_e32 v76, v35
	v_pk_add_f32 v[34:35], v[56:57], v[76:77]
	v_pk_add_f32 v[32:33], v[32:33], v[34:35]
	v_add_f32_e32 v32, v32, v33
	v_fmamk_f32 v32, v32, 0x3b000000, v148
	v_rsq_f32_e32 v253, v32
	s_nop 0
	s_nop 1
	s_nop 1
	v_mov_b32_e32 v32, v252
	v_pk_mul_f32 v[60:61], v[16:17], s[18:19] op_sel_hi:[1,0]
	v_mov_b32_e32 v33, v253
	v_pk_mul_f32 v[34:35], v[66:67], s[20:21] op_sel_hi:[1,0]
	v_pk_mul_f32 v[46:47], v[46:47], v[34:35]
	v_pk_mul_f32 v[32:33], v[32:33], s[20:21] op_sel_hi:[1,0]
	v_med3_f32 v46, v46, s69, v150
	v_med3_f32 v47, v47, s69, v150
	v_cvt_pk_fp8_f32 v56, v46, v47
	v_pk_mul_f32 v[44:45], v[44:45], v[32:33]
	v_pk_mul_f32 v[42:43], v[42:43], v[34:35]
	v_med3_f32 v44, v44, s69, v150
	v_med3_f32 v45, v45, s69, v150
	v_cvt_pk_fp8_f32 v56, v44, v45 op_sel:[0,0,1]
	v_med3_f32 v42, v42, s69, v150
	v_med3_f32 v43, v43, s69, v150
	v_cvt_pk_fp8_f32 v44, v42, v43
	v_pk_mul_f32 v[40:41], v[40:41], v[32:33]
	v_pk_mul_f32 v[36:37], v[36:37], v[34:35]
	v_med3_f32 v40, v40, s69, v150
	v_med3_f32 v41, v41, s69, v150
	v_cvt_pk_fp8_f32 v44, v40, v41 op_sel:[0,0,1]
	v_med3_f32 v36, v36, s69, v150
	v_med3_f32 v37, v37, s69, v150
	v_cvt_pk_fp8_f32 v40, v36, v37
	v_pk_mul_f32 v[36:37], v[38:39], v[32:33]
	v_pk_mul_f32 v[34:35], v[78:79], v[34:35]
	v_med3_f32 v36, v36, s69, v150
	v_med3_f32 v37, v37, s69, v150
	v_cvt_pk_fp8_f32 v40, v36, v37 op_sel:[0,0,1]
	v_med3_f32 v34, v34, s69, v150
	v_med3_f32 v35, v35, s69, v150
	v_cvt_pk_fp8_f32 v36, v34, v35
	v_pk_mul_f32 v[32:33], v[80:81], v[32:33]
	v_cvt_f32_i32_e32 v57, v31
	v_med3_f32 v32, v32, s69, v150
	v_med3_f32 v33, v33, s69, v150
	v_cvt_pk_fp8_f32 v36, v32, v33 op_sel:[0,0,1]
	v_or_b32_e32 v32, 32, v64
	v_ashrrev_i32_e32 v33, 31, v32
	v_lshlrev_b64 v[32:33], 6, v[32:33]
	global_store_dword v[48:49], v56, off offset:8
	global_store_dword v[50:51], v44, off offset:8
	global_store_dword v[52:53], v40, off offset:8
	global_store_dword v[54:55], v36, off offset:8
	v_lshl_add_u64 v[36:37], s[8:9], 0, v[32:33]
	global_load_dwordx4 v[32:35], v[36:37], off offset:32
	s_nop 0
	global_load_dwordx4 v[36:39], v[36:37], off offset:48
	v_or_b32_e32 v40, 33, v64
	v_ashrrev_i32_e32 v41, 31, v40
	v_lshlrev_b64 v[40:41], 6, v[40:41]
	v_lshl_add_u64 v[44:45], s[8:9], 0, v[40:41]
	global_load_dwordx4 v[40:43], v[44:45], off offset:32
	s_nop 0
	global_load_dwordx4 v[44:47], v[44:45], off offset:48
	v_cvt_f32_i32_e32 v56, v30
	v_pk_mul_f32 v[30:31], v[28:29], s[18:19] op_sel_hi:[1,0]
	v_pk_mul_f32 v[62:63], v[18:19], s[18:19] op_sel_hi:[1,0]
	v_pk_mul_f32 v[28:29], v[56:57], s[18:19] op_sel_hi:[1,0]
	v_cvt_f32_i32_e32 v57, v27
	v_cvt_f32_i32_e32 v56, v26
	v_pk_mul_f32 v[26:27], v[24:25], s[18:19] op_sel_hi:[1,0]
	v_pk_mul_f32 v[24:25], v[56:57], s[18:19] op_sel_hi:[1,0]
	s_waitcnt vmcnt(3)
	v_mov_b32_e32 v56, v32
	s_waitcnt vmcnt(2)
	v_mov_b32_e32 v57, v36
	v_mov_b32_e32 v36, v33
	v_pk_add_f32 v[32:33], v[56:57], v[36:37]
	v_mov_b32_e32 v36, v34
	v_mov_b32_e32 v37, v38
	v_mov_b32_e32 v38, v35
	v_pk_add_f32 v[34:35], v[36:37], v[38:39]
	s_waitcnt vmcnt(0)
	v_mov_b32_e32 v17, v44
	v_pk_add_f32 v[32:33], v[32:33], v[34:35]
	v_mov_b32_e32 v44, v41
	v_add_f32_e32 v56, v32, v33
	v_or_b32_e32 v32, 34, v64
	v_ashrrev_i32_e32 v33, 31, v32
	v_lshlrev_b64 v[32:33], 6, v[32:33]
	v_lshl_add_u64 v[36:37], s[8:9], 0, v[32:33]
	global_load_dwordx4 v[32:35], v[36:37], off offset:32
	s_nop 0
	global_load_dwordx4 v[36:39], v[36:37], off offset:48
	v_fmamk_f32 v56, v56, 0x3b000000, v148
	v_rsq_f32_e32 v246, v56
	s_nop 1
	s_nop 0
	s_nop 0
	s_nop 1
	s_nop 1
	v_mov_b32_e32 v16, v40
	v_pk_add_f32 v[40:41], v[16:17], v[44:45]
	v_or_b32_e32 v16, 35, v64
	v_ashrrev_i32_e32 v17, 31, v16
	v_lshlrev_b64 v[16:17], 6, v[16:17]
	v_lshl_add_u64 v[44:45], s[8:9], 0, v[16:17]
	global_load_dwordx4 v[16:19], v[44:45], off offset:32
	global_load_dwordx4 v[56:59], v[44:45], off offset:48
	v_mov_b32_e32 v44, v42
	v_mov_b32_e32 v45, v46
	v_mov_b32_e32 v46, v43
	v_pk_add_f32 v[42:43], v[44:45], v[46:47]
	v_pk_add_f32 v[40:41], v[40:41], v[42:43]
	v_add_f32_e32 v40, v40, v41
	v_fmamk_f32 v40, v40, 0x3b000000, v148
	v_rsq_f32_e32 v247, v40
	s_nop 0
	s_nop 0
	s_nop 1
	s_waitcnt vmcnt(2)
	v_mov_b32_e32 v43, v36
	v_mov_b32_e32 v36, v33
	v_mov_b32_e32 v42, v32
	v_pk_add_f32 v[32:33], v[42:43], v[36:37]
	v_mov_b32_e32 v36, v34
	v_mov_b32_e32 v37, v38
	v_mov_b32_e32 v38, v35
	v_pk_add_f32 v[34:35], v[36:37], v[38:39]
	v_pk_add_f32 v[32:33], v[32:33], v[34:35]
	v_add_f32_e32 v32, v32, v33
	v_fmamk_f32 v32, v32, 0x3b000000, v148
	v_rsq_f32_e32 v248, v32
	v_mov_b32_e32 v40, v246
	s_nop 0
	s_nop 1
	s_nop 1
	v_mov_b32_e32 v41, v247
	s_waitcnt vmcnt(0)
; __device__ __forceinline__ float clamp448(float x) { return __builtin_amdgcn_fmed3f(x, -448.0f, 448.0f); }
; __device__ __forceinline__ float rms_scale(const float* ssq, int row, int which) {
;     const f32x4 a = *(const f32x4*)(ssq + (size_t)row * 16 + which * 8), b = *(const f32x4*)(ssq + (size_t)row * 16 + which * 8 + 4);
;     const float s = ((a[0] + a[1]) + (a[2] + a[3])) + ((b[0] + b[1]) + (b[2] + b[3]));
;     return 1.0f / sqrtf(s * (1.0f / 512.0f) + RMS_EPS);
;     __device__ __forceinline__ void operator()(EPI_ARGS) const {
;     ...
;             for (int m = 0; m < 4; ++m) { const int t0 = u.pm * BM + ai * HALF + wr * 64 + 16 * m + 4 * fq, q = 4 * m + fq;
;                 const f32x4 rs = (f32x4){rms_scale(ssq, t0, 1), rms_scale(ssq, t0 + 1, 1), rms_scale(ssq, t0 + 2, 1), rms_scale(ssq, t0 + 3, 1)} * osc;
;                 const size_t tpos = (size_t)(t0 & ~63) + 32 * (q & 1) + 16 * (q >> 3) + 4 * ((q >> 1) & 3);
; #pragma unroll
;                 for (int bj = 0; bj < 2; ++bj)
; #pragma unroll
;                     for (int n = 0; n < 2; ++n) { const f32x4 v = acc[ai][bj][m][n] * rs;
;                         int w = __builtin_amdgcn_cvt_pk_fp8_f32(clamp448(v[0]), clamp448(v[1]), 0, false); w = __builtin_amdgcn_cvt_pk_fp8_f32(clamp448(v[2]), clamp448(v[3]), w, true);
;                         *(unsigned*)(VT + ((size_t)((2 * u.pn + bj) * 128 + dcol + 4 * n)) * NTOK + tpos) = (unsigned)w; } }
	v_mov_b32_e32 v33, v56
	v_mov_b32_e32 v32, v16
	v_mov_b32_e32 v56, v17
	v_pk_add_f32 v[16:17], v[32:33], v[56:57]
	v_mov_b32_e32 v32, v18
	v_mov_b32_e32 v33, v58
	v_mov_b32_e32 v58, v19
	v_pk_add_f32 v[18:19], v[32:33], v[58:59]
	v_pk_add_f32 v[16:17], v[16:17], v[18:19]
	v_add_f32_e32 v16, v16, v17
	v_fmamk_f32 v16, v16, 0x3b000000, v148
	v_rsq_f32_e32 v249, v16
	s_nop 0
	s_nop 1
	s_nop 1
	v_mov_b32_e32 v16, v248
	v_pk_mul_f32 v[36:37], v[0:1], s[18:19] op_sel_hi:[1,0]
	v_mov_b32_e32 v17, v249
	v_pk_mul_f32 v[18:19], v[40:41], s[20:21] op_sel_hi:[1,0]
	v_pk_mul_f32 v[30:31], v[30:31], v[18:19]
	v_pk_mul_f32 v[16:17], v[16:17], s[20:21] op_sel_hi:[1,0]
	v_med3_f32 v30, v30, s69, v150
	v_med3_f32 v31, v31, s69, v150
	v_cvt_pk_fp8_f32 v32, v30, v31
	v_pk_mul_f32 v[28:29], v[28:29], v[16:17]
	v_pk_mul_f32 v[26:27], v[26:27], v[18:19]
	v_med3_f32 v28, v28, s69, v150
	v_med3_f32 v29, v29, s69, v150
	v_cvt_pk_fp8_f32 v32, v28, v29 op_sel:[0,0,1]
	v_med3_f32 v26, v26, s69, v150
	v_med3_f32 v27, v27, s69, v150
	v_cvt_pk_fp8_f32 v28, v26, v27
	v_pk_mul_f32 v[24:25], v[24:25], v[16:17]
	v_pk_mul_f32 v[20:21], v[20:21], v[18:19]
	v_med3_f32 v24, v24, s69, v150
	v_med3_f32 v25, v25, s69, v150
	v_cvt_pk_fp8_f32 v28, v24, v25 op_sel:[0,0,1]
	v_med3_f32 v20, v20, s69, v150
	v_med3_f32 v21, v21, s69, v150
	v_cvt_pk_fp8_f32 v24, v20, v21
	v_pk_mul_f32 v[20:21], v[22:23], v[16:17]
	v_pk_mul_f32 v[18:19], v[60:61], v[18:19]
	v_med3_f32 v20, v20, s69, v150
	v_med3_f32 v21, v21, s69, v150
	v_cvt_pk_fp8_f32 v24, v20, v21 op_sel:[0,0,1]
	v_med3_f32 v18, v18, s69, v150
	v_med3_f32 v19, v19, s69, v150
	v_cvt_pk_fp8_f32 v20, v18, v19
	v_pk_mul_f32 v[16:17], v[62:63], v[16:17]
	v_cvt_f32_i32_e32 v33, v15
	v_med3_f32 v16, v16, s69, v150
	v_med3_f32 v17, v17, s69, v150
	v_cvt_pk_fp8_f32 v20, v16, v17 op_sel:[0,0,1]
	v_or_b32_e32 v16, 48, v64
	v_ashrrev_i32_e32 v17, 31, v16
	v_lshlrev_b64 v[16:17], 6, v[16:17]
	global_store_dword v[48:49], v32, off offset:16
	global_store_dword v[50:51], v28, off offset:16
	global_store_dword v[52:53], v24, off offset:16
	global_store_dword v[54:55], v20, off offset:16
	v_lshl_add_u64 v[20:21], s[8:9], 0, v[16:17]
	global_load_dwordx4 v[16:19], v[20:21], off offset:32
	s_nop 0
	global_load_dwordx4 v[20:23], v[20:21], off offset:48
	v_or_b32_e32 v24, 49, v64
	v_ashrrev_i32_e32 v25, 31, v24
	v_lshlrev_b64 v[24:25], 6, v[24:25]
	v_lshl_add_u64 v[28:29], s[8:9], 0, v[24:25]
	global_load_dwordx4 v[24:27], v[28:29], off offset:32
	s_nop 0
	global_load_dwordx4 v[28:31], v[28:29], off offset:48
	v_cvt_f32_i32_e32 v32, v14
	v_pk_mul_f32 v[14:15], v[12:13], s[18:19] op_sel_hi:[1,0]
	v_pk_mul_f32 v[38:39], v[2:3], s[18:19] op_sel_hi:[1,0]
	v_pk_mul_f32 v[12:13], v[32:33], s[18:19] op_sel_hi:[1,0]
	v_cvt_f32_i32_e32 v33, v11
	v_cvt_f32_i32_e32 v32, v10
	v_pk_mul_f32 v[10:11], v[8:9], s[18:19] op_sel_hi:[1,0]
	v_pk_mul_f32 v[8:9], v[32:33], s[18:19] op_sel_hi:[1,0]
	s_waitcnt vmcnt(3)
	v_mov_b32_e32 v32, v16
	s_waitcnt vmcnt(2)
	v_mov_b32_e32 v33, v20
	v_mov_b32_e32 v20, v17
	v_pk_add_f32 v[16:17], v[32:33], v[20:21]
	v_mov_b32_e32 v20, v18
	v_mov_b32_e32 v21, v22
	v_mov_b32_e32 v22, v19
	v_pk_add_f32 v[18:19], v[20:21], v[22:23]
	s_waitcnt vmcnt(0)
	v_mov_b32_e32 v1, v28
	v_pk_add_f32 v[16:17], v[16:17], v[18:19]
	v_mov_b32_e32 v28, v25
	v_add_f32_e32 v32, v16, v17
	v_or_b32_e32 v16, 50, v64
	v_ashrrev_i32_e32 v17, 31, v16
	v_lshlrev_b64 v[16:17], 6, v[16:17]
	v_lshl_add_u64 v[20:21], s[8:9], 0, v[16:17]
	global_load_dwordx4 v[16:19], v[20:21], off offset:32
	s_nop 0
	global_load_dwordx4 v[20:23], v[20:21], off offset:48
	v_fmamk_f32 v32, v32, 0x3b000000, v148
	v_rsq_f32_e32 v250, v32
	s_nop 1
	s_nop 0
	s_nop 0
	s_nop 1
	s_nop 1
	v_mov_b32_e32 v0, v24
	v_pk_add_f32 v[24:25], v[0:1], v[28:29]
	v_or_b32_e32 v0, 51, v64
	v_ashrrev_i32_e32 v1, 31, v0
	v_lshlrev_b64 v[0:1], 6, v[0:1]
	v_lshl_add_u64 v[28:29], s[8:9], 0, v[0:1]
	global_load_dwordx4 v[0:3], v[28:29], off offset:32
	global_load_dwordx4 v[32:35], v[28:29], off offset:48
	v_mov_b32_e32 v28, v26
	v_mov_b32_e32 v29, v30
	v_mov_b32_e32 v30, v27
	v_pk_add_f32 v[26:27], v[28:29], v[30:31]
	v_pk_add_f32 v[24:25], v[24:25], v[26:27]
	v_add_f32_e32 v24, v24, v25
	v_fmamk_f32 v24, v24, 0x3b000000, v148
	v_rsq_f32_e32 v251, v24
	s_nop 0
	s_nop 0
	s_nop 1
	s_waitcnt vmcnt(2)
	v_mov_b32_e32 v27, v20
	v_mov_b32_e32 v20, v17
	v_mov_b32_e32 v26, v16
	v_pk_add_f32 v[16:17], v[26:27], v[20:21]
	v_mov_b32_e32 v20, v18
	v_mov_b32_e32 v21, v22
	v_mov_b32_e32 v22, v19
	v_pk_add_f32 v[18:19], v[20:21], v[22:23]
	v_pk_add_f32 v[16:17], v[16:17], v[18:19]
	v_add_f32_e32 v16, v16, v17
	v_fmamk_f32 v16, v16, 0x3b000000, v148
	v_rsq_f32_e32 v252, v16
	v_mov_b32_e32 v24, v250
	s_nop 0
	s_nop 1
	s_nop 1
	v_mov_b32_e32 v25, v251
	s_waitcnt vmcnt(0)
	v_mov_b32_e32 v17, v32
	v_mov_b32_e32 v16, v0
	v_mov_b32_e32 v32, v1
	v_pk_add_f32 v[0:1], v[16:17], v[32:33]
	v_mov_b32_e32 v16, v2
	v_mov_b32_e32 v17, v34
	v_mov_b32_e32 v34, v3
	v_pk_add_f32 v[2:3], v[16:17], v[34:35]
	v_pk_add_f32 v[0:1], v[0:1], v[2:3]
	v_add_f32_e32 v0, v0, v1
	v_fmamk_f32 v0, v0, 0x3b000000, v148
	v_rsq_f32_e32 v253, v0
	s_nop 0
	s_nop 1
	s_nop 1
	v_mov_b32_e32 v0, v252
	v_mov_b32_e32 v1, v253
	v_pk_mul_f32 v[2:3], v[24:25], s[20:21] op_sel_hi:[1,0]
	v_pk_mul_f32 v[14:15], v[14:15], v[2:3]
	v_pk_mul_f32 v[0:1], v[0:1], s[20:21] op_sel_hi:[1,0]
	v_med3_f32 v14, v14, s69, v150
	v_med3_f32 v15, v15, s69, v150
	v_cvt_pk_fp8_f32 v16, v14, v15
	v_pk_mul_f32 v[12:13], v[12:13], v[0:1]
	v_pk_mul_f32 v[10:11], v[10:11], v[2:3]
	v_med3_f32 v12, v12, s69, v150
	v_med3_f32 v13, v13, s69, v150
	v_cvt_pk_fp8_f32 v16, v12, v13 op_sel:[0,0,1]
	v_med3_f32 v10, v10, s69, v150
	v_med3_f32 v11, v11, s69, v150
	v_cvt_pk_fp8_f32 v12, v10, v11
	v_pk_mul_f32 v[8:9], v[8:9], v[0:1]
	v_pk_mul_f32 v[4:5], v[4:5], v[2:3]
	v_med3_f32 v8, v8, s69, v150
	v_med3_f32 v9, v9, s69, v150
	v_cvt_pk_fp8_f32 v12, v8, v9 op_sel:[0,0,1]
	v_med3_f32 v4, v4, s69, v150
	v_med3_f32 v5, v5, s69, v150
	v_cvt_pk_fp8_f32 v8, v4, v5
	v_pk_mul_f32 v[4:5], v[6:7], v[0:1]
	v_pk_mul_f32 v[2:3], v[36:37], v[2:3]
	v_med3_f32 v4, v4, s69, v150
	v_med3_f32 v5, v5, s69, v150
	v_cvt_pk_fp8_f32 v8, v4, v5 op_sel:[0,0,1]
	v_med3_f32 v2, v2, s69, v150
	v_med3_f32 v3, v3, s69, v150
	v_cvt_pk_fp8_f32 v4, v2, v3
	v_pk_mul_f32 v[0:1], v[38:39], v[0:1]
	s_andn2_b64 vcc, exec, s[2:3]
	v_med3_f32 v0, v0, s69, v150
	v_med3_f32 v1, v1, s69, v150
	v_cvt_pk_fp8_f32 v4, v0, v1 op_sel:[0,0,1]
	s_mov_b64 s[2:3], -1
	global_store_dword v[48:49], v16, off offset:24
	global_store_dword v[50:51], v12, off offset:24
	global_store_dword v[52:53], v8, off offset:24
	global_store_dword v[54:55], v4, off offset:24
	s_cbranch_vccnz .LBB0_4154
	s_andn2_b64 vcc, exec, s[10:11]
	s_cbranch_vccnz .LBB0_4153
	s_barrier
	s_branch .LBB0_4153

; __device__ __forceinline__ f32x4 bf4x(const u32x2 a) { return (f32x4){__uint_as_float(a.x << 16), __uint_as_float(a.x & 0xffff0000u), __uint_as_float(a.y << 16), __uint_as_float(a.y & 0xffff0000u)}; }
; __device__ __forceinline__ void ln_norm2(f32x4 (&v)[8], const float* g, const float* b, int lane, float& mean_o, float& rstd_o) {
;     float s = 0.f;
; #pragma unroll
;     for (int j = 0; j < 8; ++j) s += (v[j][0] + v[j][1]) + (v[j][2] + v[j][3]);
;     const float mean = wave_sum(s) * (1.f / DM); float s2 = 0.f;
; __device__ __forceinline__ void ln3_router_phase(const Params& P, LAS unsigned char* lds, const int tid) {
;     ...
;         for (int i = 0; i < 8; ++i) { const int m = c * 64 + wave * 8 + i; asm volatile("" ::: "memory");
;             const u32x2* yr = (const u32x2*)(Y + (size_t)m * DM) + lane; f32x4 v[8];
; #pragma unroll
;             for (int j = 0; j < 8; ++j) v[j] = bf4x(yr[64 * j]);
.LBB0_4582:
	v_add_u32_e32 v68, s49, v85
	v_ashrrev_i32_e32 v69, 31, v68
	v_lshlrev_b64 v[36:37], 12, v[68:69]
	v_lshl_add_u64 v[36:37], v[10:11], 0, v[36:37]
	global_load_dwordx2 v[38:39], v[36:37], off offset:1536
	global_load_dwordx2 v[40:41], v[36:37], off offset:2048
	global_load_dwordx2 v[44:45], v[36:37], off offset:3072
	global_load_dwordx2 v[52:53], v[36:37], off offset:3584
	global_load_dwordx2 v[56:57], v[36:37], off
	global_load_dwordx2 v[62:63], v[36:37], off offset:512
	global_load_dwordx2 v[64:65], v[36:37], off offset:1024
	global_load_dwordx2 v[66:67], v[36:37], off offset:2560
	v_cmp_lt_i32_e32 vcc, v88, v87
	v_lshlrev_b64 v[68:69], 11, v[68:69]
	v_lshl_add_u64 v[68:69], v[12:13], 0, v[68:69]
	v_cndmask_b32_e32 v35, v86, v88, vcc
	v_lshlrev_b32_e32 v100, 2, v35
	v_cmp_lt_i32_e32 vcc, v89, v87
	s_waitcnt vmcnt(7)
	v_lshlrev_b32_e32 v48, 16, v38
	s_waitcnt vmcnt(6)
	v_lshlrev_b32_e32 v46, 16, v40
	v_and_b32_e32 v76, 0xffff0000, v40
	s_waitcnt vmcnt(5)
	v_lshlrev_b32_e32 v36, 16, v44
	s_waitcnt vmcnt(3)
	v_lshlrev_b32_e32 v59, 16, v56
	s_waitcnt vmcnt(2)
	v_lshlrev_b32_e32 v58, 16, v62
	v_and_b32_e32 v61, 0xffff0000, v56
	v_and_b32_e32 v60, 0xffff0000, v62
	v_lshlrev_b32_e32 v55, 16, v57
	v_lshlrev_b32_e32 v54, 16, v63
	v_and_b32_e32 v57, 0xffff0000, v57
	v_and_b32_e32 v56, 0xffff0000, v63
	v_and_b32_e32 v37, 0xffff0000, v44
	v_lshlrev_b32_e32 v44, 16, v52
	v_and_b32_e32 v72, 0xffff0000, v52
	v_lshlrev_b32_e32 v40, 16, v53
	v_and_b32_e32 v70, 0xffff0000, v53
	s_waitcnt vmcnt(1)
	v_lshlrev_b32_e32 v53, 16, v65
	v_lshlrev_b32_e32 v52, 16, v64
	v_and_b32_e32 v63, 0xffff0000, v65
	v_and_b32_e32 v62, 0xffff0000, v64
	s_waitcnt vmcnt(0)
	v_lshlrev_b32_e32 v79, 16, v67
	v_lshlrev_b32_e32 v78, 16, v66
	v_and_b32_e32 v65, 0xffff0000, v67
	v_and_b32_e32 v64, 0xffff0000, v66
	v_pk_add_f32 v[66:67], v[58:59], v[60:61]
	v_pk_add_f32 v[80:81], v[54:55], v[56:57]
	v_pk_add_f32 v[102:103], v[52:53], v[62:63]
	v_pk_add_f32 v[66:67], v[66:67], v[80:81]
	v_and_b32_e32 v49, 0xffff0000, v38
	v_lshlrev_b32_e32 v50, 16, v39
	v_and_b32_e32 v51, 0xffff0000, v39
	v_pk_add_f32 v[80:81], v[102:103], v[102:103] op_sel_hi:[0,1]
	v_add_f32_e32 v35, 0, v67
	v_lshlrev_b32_e32 v42, 16, v41
	v_and_b32_e32 v74, 0xffff0000, v41
	v_add_f32_e32 v47, v48, v49
	v_add_f32_e32 v77, v50, v51
	v_mov_b32_e32 v43, v81
	v_add_f32_e32 v75, v66, v35
	v_pk_add_f32 v[102:103], v[46:47], v[76:77]
	v_pk_add_f32 v[66:67], v[42:43], v[74:75]
	v_pk_add_f32 v[104:105], v[78:79], v[64:65]
	v_pk_add_f32 v[66:67], v[102:103], v[66:67]
	v_lshlrev_b32_e32 v38, 16, v45
	v_and_b32_e32 v39, 0xffff0000, v45
	v_pk_add_f32 v[104:105], v[104:105], v[104:105] op_sel_hi:[0,1]
	v_pk_add_f32 v[66:67], v[66:67], v[66:67] op_sel_hi:[0,1]
	v_add_f32_e32 v45, v36, v37
	v_add_f32_e32 v73, v38, v39
	v_mov_b32_e32 v41, v105
	v_mov_b32_e32 v71, v67
	v_pk_add_f32 v[106:107], v[44:45], v[72:73]
	v_pk_add_f32 v[66:67], v[40:41], v[70:71]
	v_cndmask_b32_e32 v43, v86, v89, vcc
	v_pk_add_f32 v[66:67], v[106:107], v[66:67]
	v_lshlrev_b32_e32 v71, 2, v43
	v_add_f32_e32 v35, v66, v67
	s_nop 1
	v_mov_b32_dpp v41, v35 quad_perm:[1,0,3,2] row_mask:0xf bank_mask:0xf
	v_cmp_lt_i32_e32 vcc, v90, v87
	s_waitcnt lgkmcnt(0)
	v_add_f32_e32 v35, v35, v41
	s_nop 1
	v_mov_b32_dpp v41, v35 quad_perm:[2,3,0,1] row_mask:0xf bank_mask:0xf
	v_cndmask_b32_e32 v43, v86, v90, vcc
	v_lshlrev_b32_e32 v73, 2, v43
	v_cmp_lt_i32_e32 vcc, v91, v87
	s_waitcnt lgkmcnt(0)
	v_add_f32_e32 v35, v35, v41
	s_nop 1
	v_mov_b32_dpp v41, v35 row_half_mirror row_mask:0xf bank_mask:0xf
	v_cndmask_b32_e32 v43, v86, v91, vcc
	v_lshlrev_b32_e32 v75, 2, v43
	v_cmp_lt_i32_e32 vcc, v92, v87
	s_waitcnt lgkmcnt(0)
	v_add_f32_e32 v35, v35, v41
	s_nop 1
	v_mov_b32_dpp v41, v35 row_mirror row_mask:0xf bank_mask:0xf
	v_cndmask_b32_e32 v43, v86, v92, vcc
	v_lshlrev_b32_e32 v77, 2, v43
	v_cmp_lt_i32_e32 vcc, v93, v87
	s_waitcnt lgkmcnt(0)
	v_add_f32_e32 v35, v35, v41
	ds_bpermute_b32 v41, v77, v35
	v_cndmask_b32_e32 v43, v86, v93, vcc
	v_lshlrev_b32_e32 v101, 2, v43
	s_waitcnt lgkmcnt(0)
	v_add_f32_e32 v35, v35, v41
	ds_bpermute_b32 v41, v101, v35
	s_waitcnt lgkmcnt(0)
	v_add_f32_e32 v102, v35, v41
	v_fmac_f32_e32 v57, 0xba000000, v102
	v_fmac_f32_e32 v61, 0xba000000, v102
	v_fmac_f32_e32 v56, 0xba000000, v102
	v_fmac_f32_e32 v60, 0xba000000, v102
	v_fmac_f32_e32 v55, 0xba000000, v102
	v_fmac_f32_e32 v59, 0xba000000, v102
	v_fmac_f32_e32 v54, 0xba000000, v102
	v_fmac_f32_e32 v58, 0xba000000, v102
	v_fmac_f32_e32 v62, 0xba000000, v102
	v_fmac_f32_e32 v63, 0xba000000, v102
	v_fmac_f32_e32 v53, 0xba000000, v102
	v_mov_b32_e32 v104, v61
	v_mov_b32_e32 v105, v60
	v_mov_b32_e32 v108, v57
	v_mov_b32_e32 v109, v56
	v_mov_b32_e32 v66, v59
	v_mov_b32_e32 v67, v58
	v_mov_b32_e32 v106, v55
	v_mov_b32_e32 v107, v54
	v_mov_b32_e32 v80, v53
	v_mov_b32_e32 v81, v63
	v_mov_b32_e32 v53, v62
	v_pk_mul_f32 v[62:63], v[104:105], v[104:105]
	v_pk_mul_f32 v[104:105], v[108:109], v[108:109]
	v_pk_fma_f32 v[62:63], v[66:67], v[66:67], v[62:63]
	v_pk_fma_f32 v[66:67], v[106:107], v[106:107], v[104:105]
	v_fmac_f32_e32 v52, 0xba000000, v102
	v_pk_add_f32 v[62:63], v[62:63], v[66:67]
	v_fmac_f32_e32 v48, 0xba000000, v102
	v_pk_mul_f32 v[108:109], v[80:81], v[80:81]
	v_pk_mul_f32 v[110:111], v[52:53], v[52:53]
	v_pk_add_f32 v[62:63], v[62:63], v[62:63] op_sel_hi:[0,1]
	v_fmac_f32_e32 v49, 0xba000000, v102
	v_fmac_f32_e32 v50, 0xba000000, v102
	v_pk_mov_b32 v[104:105], v[110:111], v[108:109] op_sel:[1,0]
	v_mov_b32_e32 v111, v109
	v_mul_f32_e32 v62, v48, v48
	v_fmac_f32_e32 v51, 0xba000000, v102
	v_pk_add_f32 v[66:67], v[104:105], v[110:111]
	v_pk_fma_f32 v[104:105], v[48:49], v[48:49], v[62:63] op_sel_hi:[1,1,0]
; __device__ __forceinline__ void ln_norm2(f32x4 (&v)[8], const float* g, const float* b, int lane, float& mean_o, float& rstd_o) {
;     ...
;     const float mean = wave_sum(s) * (1.f / DM); float s2 = 0.f;
; #pragma unroll
;     for (int j = 0; j < 8; ++j) { v[j] = v[j] - mean; s2 += (v[j][0] * v[j][0] + v[j][1] * v[j][1]) + (v[j][2] * v[j][2] + v[j][3] * v[j][3]); }
;     const float rstd = 1.f / sqrtf(wave_sum(s2) * (1.f / DM) + LN_EPS);
; #pragma unroll
;     for (int j = 0; j < 8; ++j) { const f32x4 gv = *((const f32x4*)g + lane + 64 * j), bv = *((const f32x4*)b + lane + 64 * j); v[j] = v[j] * rstd * gv + bv; }
	v_mul_f32_e32 v62, v50, v50
	v_pk_add_f32 v[66:67], v[66:67], v[66:67] op_sel_hi:[0,1]
	v_pk_fma_f32 v[106:107], v[50:51], v[50:51], v[62:63] op_sel_hi:[1,1,0]
	v_fmac_f32_e32 v74, 0xba000000, v102
	v_fmac_f32_e32 v42, 0xba000000, v102
	v_fmac_f32_e32 v76, 0xba000000, v102
	v_fmac_f32_e32 v46, 0xba000000, v102
	v_mul_f32_e32 v104, v46, v46
	v_mul_f32_e32 v106, v76, v76
	v_mul_f32_e32 v66, v42, v42
	v_mul_f32_e32 v62, v74, v74
	v_pk_add_f32 v[104:105], v[104:105], v[106:107]
	v_pk_add_f32 v[62:63], v[66:67], v[62:63]
	v_fmac_f32_e32 v64, 0xba000000, v102
	v_fmac_f32_e32 v65, 0xba000000, v102
	v_fmac_f32_e32 v79, 0xba000000, v102
	v_pk_add_f32 v[62:63], v[104:105], v[62:63]
	v_fmac_f32_e32 v78, 0xba000000, v102
	v_mov_b32_e32 v164, v79
	v_mov_b32_e32 v165, v65
	v_mov_b32_e32 v79, v64
	v_pk_add_f32 v[62:63], v[62:63], v[62:63] op_sel_hi:[0,1]
	v_pk_mul_f32 v[66:67], v[164:165], v[164:165]
	v_pk_mul_f32 v[64:65], v[78:79], v[78:79]
	v_fmac_f32_e32 v36, 0xba000000, v102
	v_pk_mov_b32 v[104:105], v[64:65], v[66:67] op_sel:[1,0]
	v_mov_b32_e32 v65, v67
	v_fmac_f32_e32 v37, 0xba000000, v102
	v_fmac_f32_e32 v38, 0xba000000, v102
	v_mul_f32_e32 v62, v36, v36
	v_pk_add_f32 v[64:65], v[104:105], v[64:65]
	v_fmac_f32_e32 v39, 0xba000000, v102
	v_pk_fma_f32 v[66:67], v[36:37], v[36:37], v[62:63] op_sel_hi:[1,1,0]
	v_mul_f32_e32 v62, v38, v38
	v_pk_add_f32 v[64:65], v[64:65], v[64:65] op_sel_hi:[0,1]
	v_pk_fma_f32 v[104:105], v[38:39], v[38:39], v[62:63] op_sel_hi:[1,1,0]
	v_fmac_f32_e32 v70, 0xba000000, v102
	v_fmac_f32_e32 v40, 0xba000000, v102
	v_fmac_f32_e32 v72, 0xba000000, v102
	v_fmac_f32_e32 v44, 0xba000000, v102
	v_mul_f32_e32 v66, v44, v44
	v_mul_f32_e32 v104, v72, v72
	v_mul_f32_e32 v64, v40, v40
	v_mul_f32_e32 v62, v70, v70
	v_pk_add_f32 v[66:67], v[66:67], v[104:105]
	v_pk_add_f32 v[62:63], v[64:65], v[62:63]
	v_mov_b32_e32 v166, v58
	v_pk_add_f32 v[62:63], v[66:67], v[62:63]
	v_mov_b32_e32 v58, v54
	v_add_f32_e32 v35, v62, v63
	global_load_dwordx4 v[62:65], v[14:15], off
	global_load_dwordx4 v[104:107], v[16:17], off
	global_load_dwordx4 v[108:111], v[14:15], off offset:1024
	global_load_dwordx4 v[112:115], v[16:17], off offset:1024
	global_load_dwordx4 v[116:119], v[14:15], off offset:2048
	global_load_dwordx4 v[120:123], v[16:17], off offset:2048
	global_load_dwordx4 v[124:127], v[14:15], off offset:3072
	global_load_dwordx4 v[128:131], v[16:17], off offset:3072
	global_load_dwordx4 v[132:135], v[18:19], off
	global_load_dwordx4 v[136:139], v[20:21], off
	global_load_dwordx4 v[140:143], v[22:23], off
	global_load_dwordx4 v[144:147], v[24:25], off
	global_load_dwordx4 v[148:151], v[26:27], off
	global_load_dwordx4 v[152:155], v[28:29], off
	s_nop 1
	v_mov_b32_dpp v41, v35 quad_perm:[1,0,3,2] row_mask:0xf bank_mask:0xf
	global_load_dwordx4 v[156:159], v[30:31], off
	global_load_dwordx4 v[160:163], v[32:33], off
	v_mov_b32_e32 v167, v60
	v_mov_b32_e32 v60, v59
	v_mov_b32_e32 v59, v56
	s_waitcnt lgkmcnt(0)
	v_add_f32_e32 v35, v35, v41
	s_nop 1
	v_mov_b32_dpp v41, v35 quad_perm:[2,3,0,1] row_mask:0xf bank_mask:0xf
	v_mov_b32_e32 v56, v55
	s_waitcnt lgkmcnt(0)
	v_add_f32_e32 v35, v35, v41
	s_nop 1
	v_mov_b32_dpp v41, v35 row_half_mirror row_mask:0xf bank_mask:0xf
	s_waitcnt lgkmcnt(0)
	v_add_f32_e32 v35, v35, v41
	s_nop 1
	v_mov_b32_dpp v41, v35 row_mirror row_mask:0xf bank_mask:0xf
	s_waitcnt lgkmcnt(0)
	v_add_f32_e32 v35, v35, v41
	ds_bpermute_b32 v41, v77, v35
	s_waitcnt lgkmcnt(0)
	v_add_f32_e32 v35, v35, v41
	ds_bpermute_b32 v41, v101, v35
	s_waitcnt lgkmcnt(0)
	v_add_f32_e32 v35, v35, v41
	v_fmamk_f32 v35, v35, 0x3a000000, v94
	v_rsq_f32_e32 v204, v35
	s_nop 1
	s_nop 0
	s_nop 0
	s_nop 1
	s_nop 1
	s_nop 0
	v_mov_b32_e32 v82, v204
	v_mov_b32_e32 v47, v76
	v_pk_mul_f32 v[54:55], v[60:61], v[82:83] op_sel_hi:[1,0]
	v_pk_mul_f32 v[56:57], v[56:57], v[82:83] op_sel_hi:[1,0]
	v_pk_mul_f32 v[52:53], v[52:53], v[82:83] op_sel_hi:[1,0]
	v_pk_mul_f32 v[50:51], v[50:51], v[82:83] op_sel_hi:[1,0]
	v_pk_mul_f32 v[46:47], v[46:47], v[82:83] op_sel_hi:[1,0]
	s_waitcnt vmcnt(14)
	v_pk_fma_f32 v[64:65], v[64:65], v[56:57], v[106:107]
	v_pk_fma_f32 v[66:67], v[62:63], v[54:55], v[104:105]
	v_pk_mul_f32 v[54:55], v[166:167], v[82:83] op_sel_hi:[1,0]
	v_pk_mul_f32 v[56:57], v[58:59], v[82:83] op_sel_hi:[1,0]
	s_waitcnt vmcnt(10)
	v_pk_fma_f32 v[58:59], v[116:117], v[52:53], v[120:121]
	s_waitcnt vmcnt(8)
	v_pk_fma_f32 v[52:53], v[126:127], v[50:51], v[130:131]
	s_waitcnt vmcnt(6)
	v_pk_fma_f32 v[50:51], v[132:133], v[46:47], v[136:137]
	v_pk_mul_f32 v[46:47], v[78:79], v[82:83] op_sel_hi:[1,0]
	v_pk_mul_f32 v[78:79], v[36:37], v[82:83] op_sel_hi:[1,0]
	v_pk_fma_f32 v[62:63], v[108:109], v[54:55], v[112:113]
	v_pk_mul_f32 v[54:55], v[80:81], v[82:83] op_sel_hi:[1,0]
	v_pk_mul_f32 v[36:37], v[38:39], v[82:83] op_sel_hi:[1,0]
	s_waitcnt vmcnt(2)
; __device__ __forceinline__ void ln_norm2(f32x4 (&v)[8], const float* g, const float* b, int lane, float& mean_o, float& rstd_o) {
;     ...
;     for (int j = 0; j < 8; ++j) { const f32x4 gv = *((const f32x4*)g + lane + 64 * j), bv = *((const f32x4*)b + lane + 64 * j); v[j] = v[j] * rstd * gv + bv; }
;     ...
;         for (int j = 0; j < 8; ++j) { if (f8s < 0.f) { o4[64 * j] = pg8::pack4i8(v[j] * -f8s); continue; }
; __device__ __forceinline__ void ln3_router_phase(const Params& P, LAS unsigned char* lds, const int tid) {
;     ...
;             float mu3, rs3; ln_norm2(v, P.in[19], P.in[20], lane, mu3, rs3); ln_store(v, nullptr, H3B, (size_t)m, lane, -ASC_XI8);
;             if (lane == 0) { st3[2 * m] = mu3; st3[2 * m + 1] = rs3; }
	v_pk_fma_f32 v[38:39], v[148:149], v[78:79], v[152:153]
	v_pk_mul_f32 v[78:79], v[64:65], s[38:39] op_sel_hi:[1,0]
	v_pk_mul_f32 v[80:81], v[66:67], s[38:39] op_sel_hi:[1,0]
	v_mov_b32_e32 v43, v74
	v_mov_b32_e32 v45, v72
	v_mov_b32_e32 v41, v70
	v_med3_f32 v35, v80, s39, v96
	v_med3_f32 v70, v81, s39, v96
	v_med3_f32 v72, v78, s39, v96
	v_med3_f32 v74, v79, s39, v96
	v_add_f32_e32 v35, 0x4b400000, v35
	v_add_f32_e32 v70, 0x4b400000, v70
	v_add_f32_e32 v72, 0x4b400000, v72
	v_add_f32_e32 v74, 0x4b400000, v74
	v_pk_fma_f32 v[60:61], v[110:111], v[56:57], v[114:115]
	v_perm_b32 v35, v70, v35, s42
	v_perm_b32 v70, v74, v72, s43
	v_or_b32_e32 v35, v35, v70
	v_pk_mul_f32 v[78:79], v[60:61], s[38:39] op_sel_hi:[1,0]
	v_pk_mul_f32 v[80:81], v[62:63], s[38:39] op_sel_hi:[1,0]
	global_store_dword v[68:69], v35, off
	v_med3_f32 v35, v80, s39, v96
	v_med3_f32 v70, v81, s39, v96
	v_med3_f32 v72, v78, s39, v96
	v_med3_f32 v74, v79, s39, v96
	v_add_f32_e32 v35, 0x4b400000, v35
	v_add_f32_e32 v70, 0x4b400000, v70
	v_add_f32_e32 v72, 0x4b400000, v72
	v_add_f32_e32 v74, 0x4b400000, v74
	v_pk_fma_f32 v[56:57], v[118:119], v[54:55], v[122:123]
	v_perm_b32 v35, v70, v35, s42
	v_perm_b32 v70, v74, v72, s43
	v_or_b32_e32 v35, v35, v70
	v_pk_mul_f32 v[78:79], v[56:57], s[38:39] op_sel_hi:[1,0]
	v_pk_mul_f32 v[80:81], v[58:59], s[38:39] op_sel_hi:[1,0]
	global_store_dword v[68:69], v35, off offset:256
	v_med3_f32 v35, v80, s39, v96
	v_med3_f32 v70, v81, s39, v96
	v_med3_f32 v72, v78, s39, v96
	v_med3_f32 v74, v79, s39, v96
	v_pk_mul_f32 v[48:49], v[48:49], v[82:83] op_sel_hi:[1,0]
	v_add_f32_e32 v35, 0x4b400000, v35
	v_add_f32_e32 v70, 0x4b400000, v70
	v_add_f32_e32 v72, 0x4b400000, v72
	v_add_f32_e32 v74, 0x4b400000, v74
	v_pk_fma_f32 v[54:55], v[124:125], v[48:49], v[128:129]
	v_perm_b32 v35, v70, v35, s42
	v_perm_b32 v70, v74, v72, s43
	v_or_b32_e32 v35, v35, v70
	v_pk_mul_f32 v[78:79], v[52:53], s[38:39] op_sel_hi:[1,0]
	v_pk_mul_f32 v[80:81], v[54:55], s[38:39] op_sel_hi:[1,0]
	global_store_dword v[68:69], v35, off offset:512
	v_med3_f32 v35, v80, s39, v96
	v_med3_f32 v70, v81, s39, v96
	v_med3_f32 v72, v78, s39, v96
	v_med3_f32 v74, v79, s39, v96
	v_pk_mul_f32 v[42:43], v[42:43], v[82:83] op_sel_hi:[1,0]
	v_add_f32_e32 v35, 0x4b400000, v35
	v_add_f32_e32 v70, 0x4b400000, v70
	v_add_f32_e32 v72, 0x4b400000, v72
	v_add_f32_e32 v74, 0x4b400000, v74
	v_pk_fma_f32 v[48:49], v[134:135], v[42:43], v[138:139]
	v_perm_b32 v35, v70, v35, s42
	v_perm_b32 v70, v74, v72, s43
	v_or_b32_e32 v35, v35, v70
	v_pk_mul_f32 v[78:79], v[48:49], s[38:39] op_sel_hi:[1,0]
	v_pk_mul_f32 v[80:81], v[50:51], s[38:39] op_sel_hi:[1,0]
	global_store_dword v[68:69], v35, off offset:768
	v_med3_f32 v35, v80, s39, v96
	v_med3_f32 v70, v81, s39, v96
	v_med3_f32 v72, v78, s39, v96
	v_med3_f32 v74, v79, s39, v96
	v_pk_mul_f32 v[42:43], v[164:165], v[82:83] op_sel_hi:[1,0]
	v_add_f32_e32 v35, 0x4b400000, v35
	v_add_f32_e32 v70, 0x4b400000, v70
	v_add_f32_e32 v72, 0x4b400000, v72
	v_add_f32_e32 v74, 0x4b400000, v74
	v_pk_fma_f32 v[42:43], v[142:143], v[42:43], v[146:147]
	v_pk_fma_f32 v[46:47], v[140:141], v[46:47], v[144:145]
	v_perm_b32 v35, v70, v35, s42
	v_perm_b32 v70, v74, v72, s43
	v_or_b32_e32 v35, v35, v70
	v_pk_mul_f32 v[78:79], v[42:43], s[38:39] op_sel_hi:[1,0]
	v_pk_mul_f32 v[80:81], v[46:47], s[38:39] op_sel_hi:[1,0]
	global_store_dword v[68:69], v35, off offset:1024
	v_med3_f32 v35, v80, s39, v96
	v_med3_f32 v70, v81, s39, v96
	v_med3_f32 v72, v78, s39, v96
	v_med3_f32 v74, v79, s39, v96
	v_add_f32_e32 v35, 0x4b400000, v35
	v_add_f32_e32 v70, 0x4b400000, v70
	v_add_f32_e32 v72, 0x4b400000, v72
	v_add_f32_e32 v74, 0x4b400000, v74
	v_pk_fma_f32 v[36:37], v[150:151], v[36:37], v[154:155]
	v_perm_b32 v35, v70, v35, s42
	v_perm_b32 v70, v74, v72, s43
	v_or_b32_e32 v35, v35, v70
	v_pk_mul_f32 v[78:79], v[36:37], s[38:39] op_sel_hi:[1,0]
	v_pk_mul_f32 v[80:81], v[38:39], s[38:39] op_sel_hi:[1,0]
	global_store_dword v[68:69], v35, off offset:1280
	v_med3_f32 v35, v80, s39, v96
	v_med3_f32 v70, v81, s39, v96
	v_med3_f32 v72, v78, s39, v96
	v_med3_f32 v74, v79, s39, v96
	v_pk_mul_f32 v[44:45], v[44:45], v[82:83] op_sel_hi:[1,0]
	v_pk_mul_f32 v[40:41], v[40:41], v[82:83] op_sel_hi:[1,0]
	v_add_f32_e32 v35, 0x4b400000, v35
	v_add_f32_e32 v70, 0x4b400000, v70
	v_add_f32_e32 v72, 0x4b400000, v72
	v_add_f32_e32 v74, 0x4b400000, v74
	s_waitcnt vmcnt(6)
	v_pk_fma_f32 v[40:41], v[158:159], v[40:41], v[162:163]
	v_pk_fma_f32 v[44:45], v[156:157], v[44:45], v[160:161]
	v_perm_b32 v35, v70, v35, s42
	v_perm_b32 v70, v74, v72, s43
	v_or_b32_e32 v35, v35, v70
	v_pk_mul_f32 v[78:79], v[40:41], s[38:39] op_sel_hi:[1,0]
	v_pk_mul_f32 v[80:81], v[44:45], s[38:39] op_sel_hi:[1,0]
	global_store_dword v[68:69], v35, off offset:1536
	v_med3_f32 v35, v80, s39, v96
	v_med3_f32 v70, v81, s39, v96
	v_med3_f32 v72, v78, s39, v96
	v_med3_f32 v74, v79, s39, v96
	v_add_f32_e32 v35, 0x4b400000, v35
	v_add_f32_e32 v70, 0x4b400000, v70
	v_add_f32_e32 v72, 0x4b400000, v72
	v_add_f32_e32 v74, 0x4b400000, v74
	v_perm_b32 v35, v70, v35, s42
	v_perm_b32 v70, v74, v72, s43
	v_or_b32_e32 v35, v35, v70
	global_store_dword v[68:69], v35, off offset:1792
	v_ashrrev_i32_e32 v35, 31, v34
	s_and_saveexec_b64 s[6:7], s[2:3]
	s_cbranch_execz .LBB0_4584
	v_mul_f32_e32 v68, 0x3a000000, v102
	v_lshl_add_u64 v[78:79], v[34:35], 2, s[28:29]
	v_mov_b32_e32 v69, v82
	global_store_dwordx2 v[78:79], v[68:69], off

; __device__ __forceinline__ f32x4 f84(const unsigned w) { return (f32x4){(float)(w & 0xffu), (float)((w >> 8) & 0xffu), (float)((w >> 16) & 0xffu), (float)(w >> 24)}; }
; __device__ __forceinline__ void ln4_fin_y(f32x4 (&y)[8], const unsigned (&r)[8], const unsigned char* YP, int p, int main_rows, int sk, size_t pstride, int lane) {
; #pragma unroll
;     for (int j = 0; j < 8; ++j) y[j] = f84(r[j]) - 128.f;
.LBB0_4900:
	global_load_dwordx4 v[0:3], v[14:15], off
	global_load_dwordx4 v[4:7], v[12:13], off
	global_load_dwordx4 v[184:187], v[12:13], off offset:1024
	global_load_dwordx4 v[188:191], v[14:15], off offset:1024
	global_load_dwordx4 v[192:195], v[14:15], off offset:2048
	global_load_dwordx4 v[196:199], v[12:13], off offset:2048
	global_load_dwordx4 v[200:203], v[12:13], off offset:3072
	global_load_dwordx4 v[204:207], v[14:15], off offset:3072
	global_load_dwordx4 v[208:211], v[16:17], off
	global_load_dwordx4 v[212:215], v[18:19], off
	global_load_dwordx4 v[216:219], v[20:21], off
	global_load_dwordx4 v[220:223], v[22:23], off
	global_load_dwordx4 v[224:227], v[24:25], off
	global_load_dwordx4 v[228:231], v[26:27], off
	global_load_dwordx4 v[232:235], v[28:29], off
	global_load_dwordx4 v[236:239], v[30:31], off
	v_mul_f32_e32 v162, 0x3b23d70a, v112
	v_mul_f32_e32 v112, 0x3b23d70a, v113
	v_lshlrev_b32_e32 v113, 16, v100
	v_and_b32_e32 v100, 0xffff0000, v100
	v_lshlrev_b32_e32 v183, 16, v101
	v_and_b32_e32 v101, 0xffff0000, v101
	v_lshlrev_b32_e32 v240, 16, v96
	v_and_b32_e32 v96, 0xffff0000, v96
	v_lshlrev_b32_e32 v241, 16, v97
	v_and_b32_e32 v242, 0xffff0000, v97
	v_lshlrev_b32_e32 v243, 16, v90
	v_and_b32_e32 v244, 0xffff0000, v90
	v_lshlrev_b32_e32 v245, 16, v91
	v_and_b32_e32 v246, 0xffff0000, v91
	v_lshlrev_b32_e32 v247, 16, v88
	v_and_b32_e32 v248, 0xffff0000, v88
	v_lshlrev_b32_e32 v249, 16, v89
	v_and_b32_e32 v250, 0xffff0000, v89
	v_sub_f32_e32 v89, v100, v81
	v_sub_f32_e32 v88, v113, v81
	v_sub_f32_e32 v91, v101, v81
	v_sub_f32_e32 v90, v183, v81
	v_sub_f32_e32 v97, v96, v81
	v_sub_f32_e32 v96, v240, v81
	v_sub_f32_e32 v101, v242, v81
	v_sub_f32_e32 v100, v241, v81
	v_sub_f32_e32 v241, v244, v81
	v_sub_f32_e32 v240, v243, v81
	v_sub_f32_e32 v243, v246, v81
	v_sub_f32_e32 v242, v245, v81
	v_sub_f32_e32 v245, v248, v81
	v_sub_f32_e32 v244, v247, v81
	v_sub_f32_e32 v247, v250, v81
	v_sub_f32_e32 v246, v249, v81
	v_pk_mul_f32 v[90:91], v[80:81], v[90:91] op_sel_hi:[0,1]
	v_pk_mul_f32 v[88:89], v[80:81], v[88:89] op_sel_hi:[0,1]
	v_pk_mul_f32 v[100:101], v[80:81], v[100:101] op_sel_hi:[0,1]
	v_pk_mul_f32 v[96:97], v[80:81], v[96:97] op_sel_hi:[0,1]
	v_pk_mul_f32 v[242:243], v[80:81], v[242:243] op_sel_hi:[0,1]
	v_pk_mul_f32 v[240:241], v[80:81], v[240:241] op_sel_hi:[0,1]
	v_pk_mul_f32 v[246:247], v[80:81], v[246:247] op_sel_hi:[0,1]
	v_pk_mul_f32 v[244:245], v[80:81], v[244:245] op_sel_hi:[0,1]
	s_waitcnt vmcnt(14)
	v_pk_fma_f32 v[0:1], v[88:89], v[4:5], v[0:1]
	v_pk_fma_f32 v[2:3], v[90:91], v[6:7], v[2:3]
	s_waitcnt vmcnt(12)
	v_pk_fma_f32 v[4:5], v[96:97], v[184:185], v[188:189]
	v_pk_fma_f32 v[6:7], v[100:101], v[186:187], v[190:191]
	s_waitcnt vmcnt(10)
	v_pk_fma_f32 v[88:89], v[240:241], v[196:197], v[192:193]
	v_pk_fma_f32 v[90:91], v[242:243], v[198:199], v[194:195]
	s_waitcnt vmcnt(8)
	v_pk_fma_f32 v[96:97], v[244:245], v[200:201], v[204:205]
	v_pk_fma_f32 v[100:101], v[246:247], v[202:203], v[206:207]
	v_pk_mul_f32 v[2:3], v[2:3], s[22:23] op_sel_hi:[1,0]
	v_pk_mul_f32 v[0:1], v[0:1], s[22:23] op_sel_hi:[1,0]
	v_pk_mul_f32 v[6:7], v[6:7], s[22:23] op_sel_hi:[1,0]
	v_pk_mul_f32 v[4:5], v[4:5], s[22:23] op_sel_hi:[1,0]
	v_pk_mul_f32 v[90:91], v[90:91], s[22:23] op_sel_hi:[1,0]
	v_pk_mul_f32 v[88:89], v[88:89], s[22:23] op_sel_hi:[1,0]
	v_pk_mul_f32 v[100:101], v[100:101], s[22:23] op_sel_hi:[1,0]
	v_pk_mul_f32 v[96:97], v[96:97], s[22:23] op_sel_hi:[1,0]
	v_pk_fma_f32 v[118:119], v[162:163], v[118:119], v[0:1] op_sel_hi:[0,1,1]
	v_pk_fma_f32 v[0:1], v[162:163], v[120:121], v[2:3] op_sel_hi:[0,1,1]
	v_pk_fma_f32 v[120:121], v[162:163], v[122:123], v[4:5] op_sel_hi:[0,1,1]
	v_pk_fma_f32 v[4:5], v[162:163], v[124:125], v[6:7] op_sel_hi:[0,1,1]
	v_pk_fma_f32 v[122:123], v[162:163], v[126:127], v[88:89] op_sel_hi:[0,1,1]
	v_pk_fma_f32 v[88:89], v[162:163], v[128:129], v[90:91] op_sel_hi:[0,1,1]
	v_pk_fma_f32 v[114:115], v[162:163], v[114:115], v[96:97] op_sel_hi:[0,1,1]
	v_pk_fma_f32 v[96:97], v[162:163], v[116:117], v[100:101] op_sel_hi:[0,1,1]
	v_pk_fma_f32 v[0:1], v[112:113], v[134:135], v[0:1] op_sel_hi:[0,1,1]
	v_pk_fma_f32 v[2:3], v[112:113], v[130:131], v[118:119] op_sel_hi:[0,1,1]
	v_pk_fma_f32 v[4:5], v[112:113], v[142:143], v[4:5] op_sel_hi:[0,1,1]
	v_pk_fma_f32 v[6:7], v[112:113], v[138:139], v[120:121] op_sel_hi:[0,1,1]
	v_pk_fma_f32 v[88:89], v[112:113], v[154:155], v[88:89] op_sel_hi:[0,1,1]
	v_pk_fma_f32 v[90:91], v[112:113], v[148:149], v[122:123] op_sel_hi:[0,1,1]
	v_pk_fma_f32 v[96:97], v[112:113], v[160:161], v[96:97] op_sel_hi:[0,1,1]
	v_pk_fma_f32 v[100:101], v[112:113], v[158:159], v[114:115] op_sel_hi:[0,1,1]
	v_lshlrev_b32_e32 v113, 16, v86
	v_and_b32_e32 v86, 0xffff0000, v86
	v_lshlrev_b32_e32 v114, 16, v87
	v_and_b32_e32 v115, 0xffff0000, v87
	v_sub_f32_e32 v87, v86, v81
	v_sub_f32_e32 v86, v113, v81
	v_sub_f32_e32 v115, v115, v81
	v_sub_f32_e32 v114, v114, v81
	v_pk_mul_f32 v[114:115], v[80:81], v[114:115] op_sel_hi:[0,1]
	v_pk_mul_f32 v[86:87], v[80:81], v[86:87] op_sel_hi:[0,1]
	s_waitcnt vmcnt(6)
	v_pk_fma_f32 v[86:87], v[86:87], v[208:209], v[212:213]
	v_pk_fma_f32 v[114:115], v[114:115], v[210:211], v[214:215]
	v_pk_mul_f32 v[86:87], v[86:87], s[22:23] op_sel_hi:[1,0]
	v_pk_mul_f32 v[114:115], v[114:115], s[22:23] op_sel_hi:[1,0]
	v_pk_fma_f32 v[106:107], v[162:163], v[106:107], v[86:87] op_sel_hi:[0,1,1]
	v_pk_fma_f32 v[86:87], v[162:163], v[110:111], v[114:115] op_sel_hi:[0,1,1]
	v_pk_fma_f32 v[86:87], v[112:113], v[156:157], v[86:87] op_sel_hi:[0,1,1]
	v_pk_fma_f32 v[106:107], v[112:113], v[152:153], v[106:107] op_sel_hi:[0,1,1]
	v_lshlrev_b32_e32 v110, 16, v84
	v_and_b32_e32 v84, 0xffff0000, v84
	v_lshlrev_b32_e32 v113, 16, v85
	v_and_b32_e32 v111, 0xffff0000, v85
	v_sub_f32_e32 v85, v84, v81
	v_sub_f32_e32 v84, v110, v81
	v_sub_f32_e32 v111, v111, v81
	v_sub_f32_e32 v110, v113, v81
	v_pk_mul_f32 v[110:111], v[80:81], v[110:111] op_sel_hi:[0,1]
	v_pk_mul_f32 v[84:85], v[80:81], v[84:85] op_sel_hi:[0,1]
	s_waitcnt vmcnt(4)
; __device__ __forceinline__ void ln_norm2(f32x4 (&v)[8], const float* g, const float* b, int lane, float& mean_o, float& rstd_o) {
;     float s = 0.f;
; #pragma unroll
;     for (int j = 0; j < 8; ++j) s += (v[j][0] + v[j][1]) + (v[j][2] + v[j][3]);
;     const float mean = wave_sum(s) * (1.f / DM); float s2 = 0.f;
	v_pk_fma_f32 v[84:85], v[84:85], v[216:217], v[220:221]
	v_pk_fma_f32 v[110:111], v[110:111], v[218:219], v[222:223]
	v_pk_mul_f32 v[84:85], v[84:85], s[22:23] op_sel_hi:[1,0]
	v_pk_mul_f32 v[110:111], v[110:111], s[22:23] op_sel_hi:[1,0]
	v_pk_fma_f32 v[104:105], v[162:163], v[104:105], v[84:85] op_sel_hi:[0,1,1]
	v_pk_fma_f32 v[84:85], v[162:163], v[108:109], v[110:111] op_sel_hi:[0,1,1]
	v_lshlrev_b32_e32 v108, 16, v82
	v_and_b32_e32 v82, 0xffff0000, v82
	v_lshlrev_b32_e32 v110, 16, v83
	v_and_b32_e32 v109, 0xffff0000, v83
	v_sub_f32_e32 v83, v82, v81
	v_sub_f32_e32 v82, v108, v81
	v_sub_f32_e32 v109, v109, v81
	v_sub_f32_e32 v108, v110, v81
	v_pk_mul_f32 v[108:109], v[80:81], v[108:109] op_sel_hi:[0,1]
	v_pk_mul_f32 v[82:83], v[80:81], v[82:83] op_sel_hi:[0,1]
	s_waitcnt vmcnt(2)
	v_pk_fma_f32 v[82:83], v[82:83], v[224:225], v[228:229]
	v_pk_fma_f32 v[108:109], v[108:109], v[226:227], v[230:231]
	v_pk_mul_f32 v[82:83], v[82:83], s[22:23] op_sel_hi:[1,0]
	v_pk_mul_f32 v[108:109], v[108:109], s[22:23] op_sel_hi:[1,0]
	v_pk_fma_f32 v[98:99], v[162:163], v[98:99], v[82:83] op_sel_hi:[0,1,1]
	v_pk_fma_f32 v[82:83], v[162:163], v[102:103], v[108:109] op_sel_hi:[0,1,1]
	v_lshlrev_b32_e32 v102, 16, v78
	v_and_b32_e32 v78, 0xffff0000, v78
	v_lshlrev_b32_e32 v108, 16, v79
	v_and_b32_e32 v103, 0xffff0000, v79
	v_sub_f32_e32 v79, v78, v81
	v_sub_f32_e32 v78, v102, v81
	v_sub_f32_e32 v103, v103, v81
	v_sub_f32_e32 v102, v108, v81
	v_pk_mul_f32 v[78:79], v[80:81], v[78:79] op_sel_hi:[0,1]
	v_pk_mul_f32 v[102:103], v[80:81], v[102:103] op_sel_hi:[0,1]
	s_waitcnt vmcnt(0)
	v_pk_fma_f32 v[78:79], v[78:79], v[232:233], v[236:237]
	v_pk_fma_f32 v[80:81], v[102:103], v[234:235], v[238:239]
	v_pk_mul_f32 v[78:79], v[78:79], s[22:23] op_sel_hi:[1,0]
	v_pk_mul_f32 v[80:81], v[80:81], s[22:23] op_sel_hi:[1,0]
	v_pk_fma_f32 v[94:95], v[162:163], v[94:95], v[78:79] op_sel_hi:[0,1,1]
	v_pk_fma_f32 v[78:79], v[162:163], v[92:93], v[80:81] op_sel_hi:[0,1,1]
	v_pk_fma_f32 v[80:81], v[112:113], v[132:133], v[94:95] op_sel_hi:[0,1,1]
	v_mov_b32_e32 v92, v2
	v_mov_b32_e32 v93, v6
	v_mov_b32_e32 v94, v3
	v_mov_b32_e32 v95, v7
	v_pk_add_f32 v[92:93], v[92:93], v[94:95]
	v_mov_b32_e32 v94, v0
	v_mov_b32_e32 v95, v4
	v_mov_b32_e32 v102, v1
	v_mov_b32_e32 v103, v5
	v_pk_add_f32 v[94:95], v[94:95], v[102:103]
	v_mov_b32_e32 v102, v90
	v_pk_add_f32 v[92:93], v[92:93], v[94:95]
	v_pk_mov_b32 v[94:95], v[90:91], v[88:89] op_sel:[1,0]
	v_mov_b32_e32 v103, v89
	v_pk_add_f32 v[94:95], v[94:95], v[102:103]
	v_add_f32_e32 v92, 0, v92
	v_pk_add_f32 v[94:95], v[94:95], v[94:95] op_sel:[0,1] op_sel_hi:[1,0]
	v_add_f32_e32 v92, v92, v93
	v_add_f32_e32 v102, v100, v101
	v_add_f32_e32 v108, v96, v97
	v_mov_b32_e32 v93, v106
	v_mov_b32_e32 v95, v107
	v_mov_b32_e32 v103, v86
	v_mov_b32_e32 v109, v87
	v_pk_fma_f32 v[84:85], v[112:113], v[150:151], v[84:85] op_sel_hi:[0,1,1]
	v_pk_fma_f32 v[104:105], v[112:113], v[146:147], v[104:105] op_sel_hi:[0,1,1]
	v_pk_add_f32 v[92:93], v[92:93], v[94:95]
	v_pk_add_f32 v[94:95], v[102:103], v[108:109]
	v_mov_b32_e32 v102, v104
	v_pk_add_f32 v[92:93], v[92:93], v[94:95]
	v_pk_mov_b32 v[94:95], v[104:105], v[84:85] op_sel:[1,0]
	v_mov_b32_e32 v103, v85
	v_pk_add_f32 v[94:95], v[94:95], v[102:103]
	v_pk_fma_f32 v[82:83], v[112:113], v[144:145], v[82:83] op_sel_hi:[0,1,1]
	v_pk_fma_f32 v[98:99], v[112:113], v[140:141], v[98:99] op_sel_hi:[0,1,1]
	v_pk_fma_f32 v[78:79], v[112:113], v[136:137], v[78:79] op_sel_hi:[0,1,1]
	v_pk_add_f32 v[92:93], v[92:93], v[92:93] op_sel:[0,1] op_sel_hi:[1,0]
	v_pk_add_f32 v[94:95], v[94:95], v[94:95] op_sel:[0,1] op_sel_hi:[1,0]
	v_add_f32_e32 v102, v98, v99
	v_add_f32_e32 v108, v82, v83
	v_mov_b32_e32 v93, v80
	v_mov_b32_e32 v95, v81
	v_mov_b32_e32 v103, v78
	v_mov_b32_e32 v109, v79
	v_pk_add_f32 v[92:93], v[92:93], v[94:95]
	v_pk_add_f32 v[94:95], v[102:103], v[108:109]
	s_nop 0
	v_pk_add_f32 v[92:93], v[92:93], v[94:95]
	v_xor_b32_e32 v94, 1, v164
	v_add_f32_e32 v92, v92, v93
	v_and_b32_e32 v93, 64, v164
	v_add_u32_e32 v93, 64, v93
	v_cmp_lt_i32_e32 vcc, v94, v93
	s_nop 1
	v_cndmask_b32_e32 v94, v164, v94, vcc
	v_lshlrev_b32_e32 v143, 2, v94
	s_nop 1
	v_mov_b32_dpp v94, v92 quad_perm:[1,0,3,2] row_mask:0xf bank_mask:0xf
	s_waitcnt lgkmcnt(0)
	v_add_f32_e32 v92, v92, v94
	v_xor_b32_e32 v94, 2, v164
	v_cmp_lt_i32_e32 vcc, v94, v93
	s_nop 1
	v_cndmask_b32_e32 v94, v164, v94, vcc
	v_lshlrev_b32_e32 v145, 2, v94
	s_nop 1
	v_mov_b32_dpp v94, v92 quad_perm:[2,3,0,1] row_mask:0xf bank_mask:0xf
	s_waitcnt lgkmcnt(0)
	v_add_f32_e32 v92, v92, v94
	v_xor_b32_e32 v94, 4, v164
	v_cmp_lt_i32_e32 vcc, v94, v93
	s_nop 1
	v_cndmask_b32_e32 v94, v164, v94, vcc
	v_lshlrev_b32_e32 v146, 2, v94
	s_nop 1
	v_mov_b32_dpp v94, v92 row_half_mirror row_mask:0xf bank_mask:0xf
	s_waitcnt lgkmcnt(0)
	v_add_f32_e32 v92, v92, v94
	v_xor_b32_e32 v94, 8, v164
	v_cmp_lt_i32_e32 vcc, v94, v93
	s_nop 1
	v_cndmask_b32_e32 v94, v164, v94, vcc
	v_lshlrev_b32_e32 v147, 2, v94
	s_nop 1
	v_mov_b32_dpp v94, v92 row_mirror row_mask:0xf bank_mask:0xf
	s_waitcnt lgkmcnt(0)
	v_add_f32_e32 v92, v92, v94
	v_xor_b32_e32 v94, 16, v164
	v_cmp_lt_i32_e32 vcc, v94, v93
	s_nop 1
	v_cndmask_b32_e32 v94, v164, v94, vcc
	v_lshlrev_b32_e32 v148, 2, v94
	ds_bpermute_b32 v94, v148, v92
	s_waitcnt lgkmcnt(0)
	v_add_f32_e32 v92, v92, v94
	v_xor_b32_e32 v94, 32, v164
	v_cmp_lt_i32_e32 vcc, v94, v93
	s_nop 1
	v_cndmask_b32_e32 v93, v164, v94, vcc
	v_lshlrev_b32_e32 v149, 2, v93
	ds_bpermute_b32 v93, v149, v92
	s_andn2_b64 vcc, exec, s[16:17]
	s_waitcnt lgkmcnt(0)
; __device__ __forceinline__ void ln_norm2(f32x4 (&v)[8], const float* g, const float* b, int lane, float& mean_o, float& rstd_o) {
;     ...
;     const float mean = wave_sum(s) * (1.f / DM); float s2 = 0.f;
; #pragma unroll
;     for (int j = 0; j < 8; ++j) { v[j] = v[j] - mean; s2 += (v[j][0] * v[j][0] + v[j][1] * v[j][1]) + (v[j][2] * v[j][2] + v[j][3] * v[j][3]); }
;     const float rstd = 1.f / sqrtf(wave_sum(s2) * (1.f / DM) + LN_EPS);
; #pragma unroll
;     for (int j = 0; j < 8; ++j) { const f32x4 gv = *((const f32x4*)g + lane + 64 * j), bv = *((const f32x4*)b + lane + 64 * j); v[j] = v[j] * rstd * gv + bv; }
;     mean_o = mean; rstd_o = rstd;
; }
; __device__ __forceinline__ void ln_norm(f32x4 (&v)[8], const float* g, const float* b, int lane) { float m_, r_; ln_norm2(v, g, b, lane, m_, r_); }
;     if (hf) { f32x4* o = (f32x4*)(hf + m * DM) + lane;
; #pragma unroll
;         for (int j = 0; j < 8; ++j) __builtin_nontemporal_store(v[j], o + 64 * j); }
	v_add_f32_e32 v92, v92, v93
	v_fmamk_f32 v1, v92, 0xba000000, v1
	v_fmamk_f32 v3, v92, 0xba000000, v3
	v_fmac_f32_e32 v0, 0xba000000, v92
	v_fmac_f32_e32 v2, 0xba000000, v92
	v_mul_f32_e32 v93, v3, v3
	v_mul_f32_e32 v94, v1, v1
	v_fmac_f32_e32 v93, v2, v2
	v_fmac_f32_e32 v94, v0, v0
	v_fmamk_f32 v5, v92, 0xba000000, v5
	v_fmamk_f32 v7, v92, 0xba000000, v7
	v_add_f32_e32 v93, v93, v94
	v_fmac_f32_e32 v4, 0xba000000, v92
	v_fmac_f32_e32 v6, 0xba000000, v92
	v_mul_f32_e32 v94, v7, v7
	v_mul_f32_e32 v95, v5, v5
	v_fmac_f32_e32 v94, v6, v6
	v_fmac_f32_e32 v95, v4, v4
	v_add_f32_e32 v94, v94, v95
	v_fmamk_f32 v89, v92, 0xba000000, v89
	v_fmamk_f32 v91, v92, 0xba000000, v91
	v_add_f32_e32 v93, v93, v94
	v_fmac_f32_e32 v88, 0xba000000, v92
	v_fmac_f32_e32 v90, 0xba000000, v92
	v_mul_f32_e32 v94, v91, v91
	v_mul_f32_e32 v95, v89, v89
	v_fmac_f32_e32 v94, v90, v90
	v_fmac_f32_e32 v95, v88, v88
	v_add_f32_e32 v94, v94, v95
	v_fmamk_f32 v97, v92, 0xba000000, v97
	v_fmamk_f32 v101, v92, 0xba000000, v101
	v_add_f32_e32 v93, v94, v93
	v_fmac_f32_e32 v96, 0xba000000, v92
	v_fmac_f32_e32 v100, 0xba000000, v92
	v_mul_f32_e32 v94, v101, v101
	v_mul_f32_e32 v95, v97, v97
	v_fmac_f32_e32 v94, v100, v100
	v_fmac_f32_e32 v95, v96, v96
	v_add_f32_e32 v94, v94, v95
	v_fmamk_f32 v87, v92, 0xba000000, v87
	v_fmamk_f32 v107, v92, 0xba000000, v107
	v_add_f32_e32 v93, v94, v93
	v_fmac_f32_e32 v86, 0xba000000, v92
	v_fmac_f32_e32 v106, 0xba000000, v92
	v_mul_f32_e32 v94, v107, v107
	v_mul_f32_e32 v95, v87, v87
	v_fmac_f32_e32 v94, v106, v106
	v_fmac_f32_e32 v95, v86, v86
	v_add_f32_e32 v94, v94, v95
	v_fmamk_f32 v85, v92, 0xba000000, v85
	v_fmamk_f32 v105, v92, 0xba000000, v105
	v_add_f32_e32 v93, v94, v93
	v_fmac_f32_e32 v84, 0xba000000, v92
	v_fmac_f32_e32 v104, 0xba000000, v92
	v_mul_f32_e32 v94, v105, v105
	v_mul_f32_e32 v95, v85, v85
	v_fmac_f32_e32 v94, v104, v104
	v_fmac_f32_e32 v95, v84, v84
	v_add_f32_e32 v94, v94, v95
	v_fmamk_f32 v83, v92, 0xba000000, v83
	v_fmamk_f32 v99, v92, 0xba000000, v99
	v_add_f32_e32 v93, v94, v93
	v_fmac_f32_e32 v82, 0xba000000, v92
	v_fmac_f32_e32 v98, 0xba000000, v92
	v_mul_f32_e32 v94, v99, v99
	v_mul_f32_e32 v95, v83, v83
	v_fmac_f32_e32 v94, v98, v98
	v_fmac_f32_e32 v95, v82, v82
	v_add_f32_e32 v94, v94, v95
	v_fmamk_f32 v79, v92, 0xba000000, v79
	v_fmamk_f32 v81, v92, 0xba000000, v81
	v_add_f32_e32 v93, v94, v93
	v_fmac_f32_e32 v78, 0xba000000, v92
	v_fmac_f32_e32 v80, 0xba000000, v92
	v_mul_f32_e32 v92, v81, v81
	v_mul_f32_e32 v94, v79, v79
	v_fmac_f32_e32 v92, v80, v80
	v_fmac_f32_e32 v94, v78, v78
	v_add_f32_e32 v92, v92, v94
	v_add_f32_e32 v92, v92, v93
	s_nop 1
	v_mov_b32_dpp v93, v92 quad_perm:[1,0,3,2] row_mask:0xf bank_mask:0xf
	s_waitcnt lgkmcnt(0)
	v_add_f32_e32 v92, v92, v93
	s_nop 1
	v_mov_b32_dpp v93, v92 quad_perm:[2,3,0,1] row_mask:0xf bank_mask:0xf
	s_waitcnt lgkmcnt(0)
	v_add_f32_e32 v92, v92, v93
	s_nop 1
	v_mov_b32_dpp v93, v92 row_half_mirror row_mask:0xf bank_mask:0xf
	s_waitcnt lgkmcnt(0)
	v_add_f32_e32 v92, v92, v93
	s_nop 1
	v_mov_b32_dpp v93, v92 row_mirror row_mask:0xf bank_mask:0xf
	s_waitcnt lgkmcnt(0)
	v_add_f32_e32 v92, v92, v93
	ds_bpermute_b32 v93, v148, v92
	s_waitcnt lgkmcnt(0)
	v_add_f32_e32 v92, v92, v93
	ds_bpermute_b32 v93, v149, v92
	s_cbranch_vccnz .LBB0_4902
	global_load_dwordx4 v[108:111], v[34:35], off
	global_load_dwordx4 v[112:115], v[38:39], off
	global_load_dwordx4 v[116:119], v[40:41], off
	global_load_dwordx4 v[120:123], v[42:43], off
	global_load_dwordx4 v[124:127], v[44:45], off
	global_load_dwordx4 v[128:131], v[46:47], off
	global_load_dwordx4 v[132:135], v[48:49], off
	global_load_dwordx4 v[136:139], v[50:51], off
	global_load_dwordx4 v[150:153], v[36:37], off offset:3072
	global_load_dwordx4 v[154:157], v[32:33], off offset:3072
	global_load_dwordx4 v[158:161], v[32:33], off offset:2048
	global_load_dwordx4 v[184:187], v[36:37], off offset:2048
	global_load_dwordx4 v[188:191], v[36:37], off offset:1024
	global_load_dwordx4 v[192:195], v[32:33], off offset:1024
	global_load_dwordx4 v[196:199], v[32:33], off
	global_load_dwordx4 v[200:203], v[36:37], off
	s_waitcnt lgkmcnt(0)
	v_add_f32_e32 v92, v92, v93
	v_fmamk_f32 v92, v92, 0x3a000000, v165
	v_rsq_f32_e32 v251, v92
	s_nop 1
	s_nop 0
	s_nop 1
	v_lshlrev_b64 v[102:103], 13, v[8:9]
	v_lshl_add_u64 v[102:103], v[52:53], 0, v[102:103]
	s_nop 1
	v_mov_b32_e32 v92, v251
	v_pk_mul_f32 v[80:81], v[80:81], v[92:93] op_sel_hi:[1,0]
	v_pk_mul_f32 v[78:79], v[78:79], v[92:93] op_sel_hi:[1,0]
	v_pk_mul_f32 v[94:95], v[98:99], v[92:93] op_sel_hi:[1,0]
	v_pk_mul_f32 v[98:99], v[104:105], v[92:93] op_sel_hi:[1,0]
	v_pk_mul_f32 v[84:85], v[84:85], v[92:93] op_sel_hi:[1,0]
	v_pk_mul_f32 v[86:87], v[86:87], v[92:93] op_sel_hi:[1,0]
	v_pk_mul_f32 v[100:101], v[100:101], v[92:93] op_sel_hi:[1,0]
	v_pk_mul_f32 v[206:207], v[2:3], v[92:93] op_sel_hi:[1,0]
	v_pk_mul_f32 v[208:209], v[0:1], v[92:93] op_sel_hi:[1,0]
	v_pk_mul_f32 v[104:105], v[106:107], v[92:93] op_sel_hi:[1,0]
	v_pk_mul_f32 v[96:97], v[96:97], v[92:93] op_sel_hi:[1,0]
	v_pk_mul_f32 v[90:91], v[90:91], v[92:93] op_sel_hi:[1,0]
	v_pk_mul_f32 v[106:107], v[88:89], v[92:93] op_sel_hi:[1,0]
	v_pk_mul_f32 v[140:141], v[6:7], v[92:93] op_sel_hi:[1,0]
	v_pk_mul_f32 v[204:205], v[4:5], v[92:93] op_sel_hi:[1,0]
	v_pk_mul_f32 v[82:83], v[82:83], v[92:93] op_sel_hi:[1,0]
	s_waitcnt vmcnt(14)
	v_pk_fma_f32 v[2:3], v[78:79], v[114:115], v[110:111]
	v_pk_fma_f32 v[0:1], v[80:81], v[112:113], v[108:109]
	s_waitcnt vmcnt(12)
	v_pk_fma_f32 v[4:5], v[94:95], v[120:121], v[116:117]
	v_pk_fma_f32 v[6:7], v[82:83], v[122:123], v[118:119]
	s_waitcnt vmcnt(10)
	v_pk_fma_f32 v[80:81], v[84:85], v[130:131], v[126:127]
	v_pk_fma_f32 v[78:79], v[98:99], v[128:129], v[124:125]
	s_waitcnt vmcnt(8)
	v_pk_fma_f32 v[84:85], v[86:87], v[138:139], v[134:135]
	v_pk_fma_f32 v[82:83], v[104:105], v[136:137], v[132:133]
	s_waitcnt vmcnt(6)
	v_pk_fma_f32 v[86:87], v[100:101], v[150:151], v[154:155]
	v_pk_fma_f32 v[88:89], v[96:97], v[152:153], v[156:157]
	s_waitcnt vmcnt(4)
	v_pk_fma_f32 v[92:93], v[106:107], v[186:187], v[160:161]
	v_pk_fma_f32 v[90:91], v[90:91], v[184:185], v[158:159]
	s_waitcnt vmcnt(2)
	v_pk_fma_f32 v[96:97], v[204:205], v[190:191], v[194:195]
	v_pk_fma_f32 v[94:95], v[140:141], v[188:189], v[192:193]
	s_waitcnt vmcnt(0)
	v_pk_fma_f32 v[100:101], v[208:209], v[202:203], v[198:199]
	v_pk_fma_f32 v[98:99], v[206:207], v[200:201], v[196:197]
	global_store_dwordx4 v[102:103], v[98:101], off nt
	global_store_dwordx4 v[102:103], v[94:97], off offset:1024 nt
	global_store_dwordx4 v[102:103], v[90:93], off offset:2048 nt
	global_store_dwordx4 v[102:103], v[86:89], off offset:3072 nt
	s_nop 1
	v_add_co_u32_e32 v86, vcc, 0x1000, v102
	s_nop 1
	v_addc_co_u32_e32 v87, vcc, 0, v103, vcc
	global_store_dwordx4 v[86:87], v[82:85], off nt
	global_store_dwordx4 v[86:87], v[78:81], off offset:1024 nt
	global_store_dwordx4 v[86:87], v[4:7], off offset:2048 nt
	global_store_dwordx4 v[86:87], v[0:3], off offset:3072 nt

.LBB0_4908:
	global_load_dwordx4 v[0:3], v[14:15], off
	global_load_dwordx4 v[4:7], v[12:13], off
	global_load_dwordx4 v[150:153], v[12:13], off offset:1024
	global_load_dwordx4 v[154:157], v[14:15], off offset:1024
	global_load_dwordx4 v[158:161], v[14:15], off offset:2048
	global_load_dwordx4 v[168:171], v[12:13], off offset:2048
	global_load_dwordx4 v[172:175], v[12:13], off offset:3072
	global_load_dwordx4 v[176:179], v[14:15], off offset:3072
	global_load_dwordx4 v[180:183], v[16:17], off
	global_load_dwordx4 v[184:187], v[18:19], off
	global_load_dwordx4 v[188:191], v[20:21], off
	global_load_dwordx4 v[192:195], v[22:23], off
	global_load_dwordx4 v[196:199], v[24:25], off
	global_load_dwordx4 v[200:203], v[26:27], off
	global_load_dwordx4 v[204:207], v[28:29], off
	global_load_dwordx4 v[208:211], v[30:31], off
	v_lshlrev_b32_e32 v9, 16, v74
	v_and_b32_e32 v74, 0xffff0000, v74
	v_mul_f32_e32 v144, 0x3b23d70a, v76
	v_mul_f32_e32 v142, 0x3b23d70a, v77
	v_lshlrev_b32_e32 v76, 16, v75
	v_and_b32_e32 v75, 0xffff0000, v75
	v_lshlrev_b32_e32 v77, 16, v72
	v_and_b32_e32 v72, 0xffff0000, v72
	v_lshlrev_b32_e32 v212, 16, v70
	v_and_b32_e32 v213, 0xffff0000, v70
	v_lshlrev_b32_e32 v214, 16, v71
	v_and_b32_e32 v215, 0xffff0000, v71
	v_lshlrev_b32_e32 v216, 16, v68
	v_and_b32_e32 v217, 0xffff0000, v68
	v_lshlrev_b32_e32 v218, 16, v69
	v_and_b32_e32 v219, 0xffff0000, v69
	v_sub_f32_e32 v69, v74, v58
	v_sub_f32_e32 v68, v9, v58
	v_lshlrev_b32_e32 v162, 16, v73
	v_and_b32_e32 v167, 0xffff0000, v73
	v_sub_f32_e32 v71, v75, v58
	v_sub_f32_e32 v70, v76, v58
	v_sub_f32_e32 v73, v72, v58
	v_sub_f32_e32 v72, v77, v58
	v_sub_f32_e32 v77, v213, v58
	v_sub_f32_e32 v76, v212, v58
	v_sub_f32_e32 v213, v215, v58
	v_sub_f32_e32 v212, v214, v58
	v_sub_f32_e32 v215, v217, v58
	v_sub_f32_e32 v214, v216, v58
	v_pk_mul_f32 v[68:69], v[58:59], v[68:69] op_sel:[1,0]
	v_sub_f32_e32 v75, v167, v58
	v_sub_f32_e32 v74, v162, v58
	v_sub_f32_e32 v217, v219, v58
	v_sub_f32_e32 v216, v218, v58
	v_pk_mul_f32 v[70:71], v[58:59], v[70:71] op_sel:[1,0]
	v_pk_mul_f32 v[72:73], v[58:59], v[72:73] op_sel:[1,0]
	v_pk_mul_f32 v[214:215], v[58:59], v[214:215] op_sel:[1,0]
	v_pk_mul_f32 v[74:75], v[58:59], v[74:75] op_sel:[1,0]
	v_pk_mul_f32 v[76:77], v[58:59], v[76:77] op_sel:[1,0]
	v_pk_mul_f32 v[216:217], v[58:59], v[216:217] op_sel:[1,0]
	v_lshlrev_b32_e32 v9, 16, v66
	v_and_b32_e32 v66, 0xffff0000, v66
	v_pk_mul_f32 v[212:213], v[58:59], v[212:213] op_sel:[1,0]
	s_nor_b64 s[0:1], s[0:1], s[14:15]
	s_waitcnt vmcnt(14)
	v_pk_fma_f32 v[0:1], v[68:69], v[4:5], v[0:1]
	v_pk_fma_f32 v[2:3], v[70:71], v[6:7], v[2:3]
	s_waitcnt vmcnt(12)
	v_pk_fma_f32 v[4:5], v[72:73], v[150:151], v[154:155]
	v_pk_mul_f32 v[0:1], v[0:1], s[22:23] op_sel_hi:[1,0]
	v_pk_fma_f32 v[6:7], v[74:75], v[152:153], v[156:157]
	s_waitcnt vmcnt(10)
	v_pk_fma_f32 v[68:69], v[76:77], v[168:169], v[158:159]
	s_waitcnt vmcnt(8)
	v_pk_fma_f32 v[72:73], v[214:215], v[172:173], v[176:177]
	v_pk_fma_f32 v[74:75], v[216:217], v[174:175], v[178:179]
	v_pk_mul_f32 v[2:3], v[2:3], s[22:23] op_sel_hi:[1,0]
	v_pk_fma_f32 v[76:77], v[144:145], v[78:79], v[0:1] op_sel_hi:[0,1,1]
	v_pk_mul_f32 v[72:73], v[72:73], s[22:23] op_sel_hi:[1,0]
	v_pk_fma_f32 v[0:1], v[144:145], v[84:85], v[2:3] op_sel_hi:[0,1,1]
	v_pk_fma_f32 v[2:3], v[142:143], v[110:111], v[76:77] op_sel_hi:[0,1,1]
	v_pk_mul_f32 v[74:75], v[74:75], s[22:23] op_sel_hi:[1,0]
	v_pk_fma_f32 v[76:77], v[144:145], v[106:107], v[72:73] op_sel_hi:[0,1,1]
	v_pk_fma_f32 v[72:73], v[144:145], v[108:109], v[74:75] op_sel_hi:[0,1,1]
	v_pk_fma_f32 v[74:75], v[142:143], v[138:139], v[76:77] op_sel_hi:[0,1,1]
	v_lshlrev_b32_e32 v76, 16, v67
	v_and_b32_e32 v77, 0xffff0000, v67
	v_sub_f32_e32 v67, v66, v58
	v_sub_f32_e32 v66, v9, v58
	v_sub_f32_e32 v77, v77, v58
	v_sub_f32_e32 v76, v76, v58
	v_pk_mul_f32 v[66:67], v[58:59], v[66:67] op_sel:[1,0]
	v_pk_mul_f32 v[4:5], v[4:5], s[22:23] op_sel_hi:[1,0]
	v_pk_mul_f32 v[76:77], v[58:59], v[76:77] op_sel:[1,0]
	s_waitcnt vmcnt(6)
	v_pk_fma_f32 v[66:67], v[66:67], v[180:181], v[184:185]
	v_pk_mul_f32 v[6:7], v[6:7], s[22:23] op_sel_hi:[1,0]
	v_pk_fma_f32 v[78:79], v[144:145], v[88:89], v[4:5] op_sel_hi:[0,1,1]
	v_pk_fma_f32 v[76:77], v[76:77], v[182:183], v[186:187]
	v_pk_mul_f32 v[66:67], v[66:67], s[22:23] op_sel_hi:[1,0]
	v_pk_fma_f32 v[4:5], v[144:145], v[92:93], v[6:7] op_sel_hi:[0,1,1]
	v_pk_fma_f32 v[6:7], v[142:143], v[118:119], v[78:79] op_sel_hi:[0,1,1]
	v_pk_mul_f32 v[76:77], v[76:77], s[22:23] op_sel_hi:[1,0]
	v_pk_fma_f32 v[78:79], v[144:145], v[98:99], v[66:67] op_sel_hi:[0,1,1]
	v_lshlrev_b32_e32 v9, 16, v64
	v_and_b32_e32 v64, 0xffff0000, v64
	v_pk_fma_f32 v[66:67], v[144:145], v[100:101], v[76:77] op_sel_hi:[0,1,1]
	v_pk_fma_f32 v[76:77], v[142:143], v[132:133], v[78:79] op_sel_hi:[0,1,1]
	v_lshlrev_b32_e32 v78, 16, v65
	v_and_b32_e32 v79, 0xffff0000, v65
	v_sub_f32_e32 v65, v64, v58
	v_sub_f32_e32 v64, v9, v58
	v_sub_f32_e32 v79, v79, v58
	v_sub_f32_e32 v78, v78, v58
	v_pk_mul_f32 v[64:65], v[58:59], v[64:65] op_sel:[1,0]
	v_pk_fma_f32 v[70:71], v[212:213], v[170:171], v[160:161]
	v_pk_mul_f32 v[68:69], v[68:69], s[22:23] op_sel_hi:[1,0]
	v_pk_mul_f32 v[78:79], v[58:59], v[78:79] op_sel:[1,0]
	s_waitcnt vmcnt(4)
; __device__ __forceinline__ void ln_norm2(f32x4 (&v)[8], const float* g, const float* b, int lane, float& mean_o, float& rstd_o) {
;     float s = 0.f;
; #pragma unroll
;     for (int j = 0; j < 8; ++j) s += (v[j][0] + v[j][1]) + (v[j][2] + v[j][3]);
;     const float mean = wave_sum(s) * (1.f / DM); float s2 = 0.f;
	v_pk_fma_f32 v[64:65], v[64:65], v[188:189], v[192:193]
	v_pk_mul_f32 v[70:71], v[70:71], s[22:23] op_sel_hi:[1,0]
	v_pk_fma_f32 v[84:85], v[144:145], v[102:103], v[68:69] op_sel_hi:[0,1,1]
	v_pk_fma_f32 v[78:79], v[78:79], v[190:191], v[194:195]
	v_pk_mul_f32 v[64:65], v[64:65], s[22:23] op_sel_hi:[1,0]
	v_pk_fma_f32 v[68:69], v[144:145], v[104:105], v[70:71] op_sel_hi:[0,1,1]
	v_pk_fma_f32 v[70:71], v[142:143], v[128:129], v[84:85] op_sel_hi:[0,1,1]
	v_pk_mul_f32 v[78:79], v[78:79], s[22:23] op_sel_hi:[1,0]
	v_pk_fma_f32 v[84:85], v[144:145], v[94:95], v[64:65] op_sel_hi:[0,1,1]
	v_lshlrev_b32_e32 v9, 16, v62
	v_and_b32_e32 v62, 0xffff0000, v62
	v_pk_fma_f32 v[64:65], v[144:145], v[96:97], v[78:79] op_sel_hi:[0,1,1]
	v_pk_fma_f32 v[78:79], v[142:143], v[126:127], v[84:85] op_sel_hi:[0,1,1]
	v_lshlrev_b32_e32 v84, 16, v63
	v_and_b32_e32 v85, 0xffff0000, v63
	v_sub_f32_e32 v63, v62, v58
	v_sub_f32_e32 v62, v9, v58
	v_sub_f32_e32 v85, v85, v58
	v_sub_f32_e32 v84, v84, v58
	v_pk_mul_f32 v[62:63], v[58:59], v[62:63] op_sel:[1,0]
	v_pk_mul_f32 v[84:85], v[58:59], v[84:85] op_sel:[1,0]
	s_waitcnt vmcnt(2)
	v_pk_fma_f32 v[62:63], v[62:63], v[196:197], v[200:201]
	v_pk_fma_f32 v[84:85], v[84:85], v[198:199], v[202:203]
	v_pk_mul_f32 v[62:63], v[62:63], s[22:23] op_sel_hi:[1,0]
	v_pk_mul_f32 v[84:85], v[84:85], s[22:23] op_sel_hi:[1,0]
	v_pk_fma_f32 v[86:87], v[144:145], v[86:87], v[62:63] op_sel_hi:[0,1,1]
	v_pk_fma_f32 v[62:63], v[144:145], v[90:91], v[84:85] op_sel_hi:[0,1,1]
	v_pk_fma_f32 v[84:85], v[142:143], v[120:121], v[86:87] op_sel_hi:[0,1,1]
	v_lshlrev_b32_e32 v9, 16, v60
	v_and_b32_e32 v60, 0xffff0000, v60
	v_lshlrev_b32_e32 v86, 16, v61
	v_and_b32_e32 v87, 0xffff0000, v61
	v_sub_f32_e32 v61, v60, v58
	v_sub_f32_e32 v60, v9, v58
	v_sub_f32_e32 v87, v87, v58
	v_sub_f32_e32 v86, v86, v58
	v_pk_mul_f32 v[86:87], v[58:59], v[86:87] op_sel:[1,0]
	v_pk_mul_f32 v[58:59], v[58:59], v[60:61] op_sel:[1,0]
	s_waitcnt vmcnt(0)
	v_pk_fma_f32 v[60:61], v[86:87], v[206:207], v[210:211]
	v_pk_fma_f32 v[58:59], v[58:59], v[204:205], v[208:209]
	v_pk_mul_f32 v[60:61], v[60:61], s[22:23] op_sel_hi:[1,0]
	v_pk_mul_f32 v[58:59], v[58:59], s[22:23] op_sel_hi:[1,0]
	v_pk_fma_f32 v[0:1], v[142:143], v[114:115], v[0:1] op_sel_hi:[0,1,1]
	v_pk_fma_f32 v[82:83], v[144:145], v[82:83], v[58:59] op_sel_hi:[0,1,1]
	v_pk_fma_f32 v[4:5], v[142:143], v[122:123], v[4:5] op_sel_hi:[0,1,1]
	v_pk_fma_f32 v[58:59], v[144:145], v[80:81], v[60:61] op_sel_hi:[0,1,1]
	v_pk_fma_f32 v[60:61], v[142:143], v[112:113], v[82:83] op_sel_hi:[0,1,1]
	v_mov_b32_e32 v80, v2
	v_mov_b32_e32 v81, v6
	v_mov_b32_e32 v82, v3
	v_mov_b32_e32 v83, v7
	v_pk_add_f32 v[80:81], v[80:81], v[82:83]
	v_mov_b32_e32 v82, v0
	v_mov_b32_e32 v83, v4
	v_mov_b32_e32 v86, v1
	v_mov_b32_e32 v87, v5
	v_pk_fma_f32 v[68:69], v[142:143], v[134:135], v[68:69] op_sel_hi:[0,1,1]
	v_pk_add_f32 v[82:83], v[82:83], v[86:87]
	v_mov_b32_e32 v86, v70
	v_pk_add_f32 v[80:81], v[80:81], v[82:83]
	v_pk_mov_b32 v[82:83], v[70:71], v[68:69] op_sel:[1,0]
	v_mov_b32_e32 v87, v69
	v_pk_add_f32 v[82:83], v[82:83], v[86:87]
	v_pk_fma_f32 v[72:73], v[142:143], v[140:141], v[72:73] op_sel_hi:[0,1,1]
	v_pk_fma_f32 v[66:67], v[142:143], v[136:137], v[66:67] op_sel_hi:[0,1,1]
	v_add_f32_e32 v9, 0, v80
	v_pk_add_f32 v[82:83], v[82:83], v[82:83] op_sel:[0,1] op_sel_hi:[1,0]
	v_add_f32_e32 v80, v9, v81
	v_add_f32_e32 v86, v74, v75
	v_add_f32_e32 v88, v72, v73
	v_mov_b32_e32 v81, v76
	v_mov_b32_e32 v83, v77
	v_mov_b32_e32 v87, v66
	v_mov_b32_e32 v89, v67
	v_pk_fma_f32 v[64:65], v[142:143], v[130:131], v[64:65] op_sel_hi:[0,1,1]
	v_pk_add_f32 v[80:81], v[80:81], v[82:83]
	v_pk_add_f32 v[82:83], v[86:87], v[88:89]
	v_mov_b32_e32 v86, v78
	v_pk_add_f32 v[80:81], v[80:81], v[82:83]
	v_pk_mov_b32 v[82:83], v[78:79], v[64:65] op_sel:[1,0]
	v_mov_b32_e32 v87, v65
	v_pk_add_f32 v[82:83], v[82:83], v[86:87]
	v_pk_fma_f32 v[62:63], v[142:143], v[124:125], v[62:63] op_sel_hi:[0,1,1]
	v_pk_fma_f32 v[58:59], v[142:143], v[116:117], v[58:59] op_sel_hi:[0,1,1]
	v_pk_add_f32 v[80:81], v[80:81], v[80:81] op_sel:[0,1] op_sel_hi:[1,0]
	v_pk_add_f32 v[82:83], v[82:83], v[82:83] op_sel:[0,1] op_sel_hi:[1,0]
	v_add_f32_e32 v86, v84, v85
	v_add_f32_e32 v88, v62, v63
	v_mov_b32_e32 v81, v60
	v_mov_b32_e32 v83, v61
	v_mov_b32_e32 v87, v58
	v_mov_b32_e32 v89, v59
	v_pk_add_f32 v[80:81], v[80:81], v[82:83]
	v_pk_add_f32 v[82:83], v[86:87], v[88:89]
	s_nop 0
	v_pk_add_f32 v[80:81], v[80:81], v[82:83]
	s_nop 0
	v_add_f32_e32 v9, v80, v81
	s_nop 1
	v_mov_b32_dpp v80, v9 quad_perm:[1,0,3,2] row_mask:0xf bank_mask:0xf
	s_waitcnt lgkmcnt(0)
	v_add_f32_e32 v9, v9, v80
	s_nop 1
	v_mov_b32_dpp v80, v9 quad_perm:[2,3,0,1] row_mask:0xf bank_mask:0xf
	s_waitcnt lgkmcnt(0)
	v_add_f32_e32 v9, v9, v80
	s_nop 1
	v_mov_b32_dpp v80, v9 row_half_mirror row_mask:0xf bank_mask:0xf
	s_waitcnt lgkmcnt(0)
	v_add_f32_e32 v9, v9, v80
	s_nop 1
	v_mov_b32_dpp v80, v9 row_mirror row_mask:0xf bank_mask:0xf
	s_waitcnt lgkmcnt(0)
	v_add_f32_e32 v9, v9, v80
	ds_bpermute_b32 v80, v148, v9
	s_waitcnt lgkmcnt(0)
	v_add_f32_e32 v9, v9, v80
	ds_bpermute_b32 v80, v149, v9
	s_waitcnt lgkmcnt(0)
; __device__ __forceinline__ void ln_norm2(f32x4 (&v)[8], const float* g, const float* b, int lane, float& mean_o, float& rstd_o) {
;     ...
;     const float mean = wave_sum(s) * (1.f / DM); float s2 = 0.f;
; #pragma unroll
;     for (int j = 0; j < 8; ++j) { v[j] = v[j] - mean; s2 += (v[j][0] * v[j][0] + v[j][1] * v[j][1]) + (v[j][2] * v[j][2] + v[j][3] * v[j][3]); }
;     const float rstd = 1.f / sqrtf(wave_sum(s2) * (1.f / DM) + LN_EPS);
; #pragma unroll
;     for (int j = 0; j < 8; ++j) { const f32x4 gv = *((const f32x4*)g + lane + 64 * j), bv = *((const f32x4*)b + lane + 64 * j); v[j] = v[j] * rstd * gv + bv; }
;     mean_o = mean; rstd_o = rstd;
; }
; __device__ __forceinline__ void ln_norm(f32x4 (&v)[8], const float* g, const float* b, int lane) { float m_, r_; ln_norm2(v, g, b, lane, m_, r_); }
;     if (hf) { f32x4* o = (f32x4*)(hf + m * DM) + lane;
; #pragma unroll
;         for (int j = 0; j < 8; ++j) __builtin_nontemporal_store(v[j], o + 64 * j); }
	v_add_f32_e32 v9, v9, v80
	v_fmamk_f32 v1, v9, 0xba000000, v1
	v_fmamk_f32 v3, v9, 0xba000000, v3
	v_fmac_f32_e32 v0, 0xba000000, v9
	v_fmac_f32_e32 v2, 0xba000000, v9
	v_mul_f32_e32 v80, v3, v3
	v_mul_f32_e32 v81, v1, v1
	v_fmac_f32_e32 v80, v2, v2
	v_fmac_f32_e32 v81, v0, v0
	v_fmamk_f32 v5, v9, 0xba000000, v5
	v_fmamk_f32 v7, v9, 0xba000000, v7
	v_add_f32_e32 v80, v80, v81
	v_fmac_f32_e32 v4, 0xba000000, v9
	v_fmac_f32_e32 v6, 0xba000000, v9
	v_mul_f32_e32 v81, v7, v7
	v_mul_f32_e32 v82, v5, v5
	v_fmac_f32_e32 v81, v6, v6
	v_fmac_f32_e32 v82, v4, v4
	v_add_f32_e32 v81, v81, v82
	v_fmamk_f32 v69, v9, 0xba000000, v69
	v_fmamk_f32 v71, v9, 0xba000000, v71
	v_add_f32_e32 v80, v80, v81
	v_fmac_f32_e32 v68, 0xba000000, v9
	v_fmac_f32_e32 v70, 0xba000000, v9
	v_mul_f32_e32 v81, v71, v71
	v_mul_f32_e32 v82, v69, v69
	v_fmac_f32_e32 v81, v70, v70
	v_fmac_f32_e32 v82, v68, v68
	v_add_f32_e32 v81, v81, v82
	v_fmamk_f32 v73, v9, 0xba000000, v73
	v_fmamk_f32 v75, v9, 0xba000000, v75
	v_add_f32_e32 v80, v81, v80
	v_fmac_f32_e32 v72, 0xba000000, v9
	v_fmac_f32_e32 v74, 0xba000000, v9
	v_mul_f32_e32 v81, v75, v75
	v_mul_f32_e32 v82, v73, v73
	v_fmac_f32_e32 v81, v74, v74
	v_fmac_f32_e32 v82, v72, v72
	v_add_f32_e32 v81, v81, v82
	v_fmamk_f32 v67, v9, 0xba000000, v67
	v_fmamk_f32 v77, v9, 0xba000000, v77
	v_add_f32_e32 v80, v81, v80
	v_fmac_f32_e32 v66, 0xba000000, v9
	v_fmac_f32_e32 v76, 0xba000000, v9
	v_mul_f32_e32 v81, v77, v77
	v_mul_f32_e32 v82, v67, v67
	v_fmac_f32_e32 v81, v76, v76
	v_fmac_f32_e32 v82, v66, v66
	v_add_f32_e32 v81, v81, v82
	v_fmamk_f32 v65, v9, 0xba000000, v65
	v_fmamk_f32 v79, v9, 0xba000000, v79
	v_add_f32_e32 v80, v81, v80
	v_fmac_f32_e32 v64, 0xba000000, v9
	v_fmac_f32_e32 v78, 0xba000000, v9
	v_mul_f32_e32 v81, v79, v79
	v_mul_f32_e32 v82, v65, v65
	v_fmac_f32_e32 v81, v78, v78
	v_fmac_f32_e32 v82, v64, v64
	v_add_f32_e32 v81, v81, v82
	v_fmamk_f32 v63, v9, 0xba000000, v63
	v_fmamk_f32 v85, v9, 0xba000000, v85
	v_add_f32_e32 v80, v81, v80
	v_fmac_f32_e32 v62, 0xba000000, v9
	v_fmac_f32_e32 v84, 0xba000000, v9
	v_mul_f32_e32 v81, v85, v85
	v_mul_f32_e32 v82, v63, v63
	v_fmac_f32_e32 v81, v84, v84
	v_fmac_f32_e32 v82, v62, v62
	v_add_f32_e32 v81, v81, v82
	v_fmamk_f32 v59, v9, 0xba000000, v59
	v_fmamk_f32 v61, v9, 0xba000000, v61
	v_add_f32_e32 v80, v81, v80
	v_fmac_f32_e32 v58, 0xba000000, v9
	v_fmac_f32_e32 v60, 0xba000000, v9
	v_mul_f32_e32 v9, v61, v61
	v_mul_f32_e32 v81, v59, v59
	v_fmac_f32_e32 v9, v60, v60
	v_fmac_f32_e32 v81, v58, v58
	v_add_f32_e32 v9, v9, v81
	v_add_f32_e32 v9, v9, v80
	s_nop 1
	v_mov_b32_dpp v80, v9 quad_perm:[1,0,3,2] row_mask:0xf bank_mask:0xf
	s_waitcnt lgkmcnt(0)
	v_add_f32_e32 v9, v9, v80
	s_nop 1
	v_mov_b32_dpp v80, v9 quad_perm:[2,3,0,1] row_mask:0xf bank_mask:0xf
	s_waitcnt lgkmcnt(0)
	v_add_f32_e32 v9, v9, v80
	s_nop 1
	v_mov_b32_dpp v80, v9 row_half_mirror row_mask:0xf bank_mask:0xf
	s_waitcnt lgkmcnt(0)
	v_add_f32_e32 v9, v9, v80
	s_nop 1
	v_mov_b32_dpp v80, v9 row_mirror row_mask:0xf bank_mask:0xf
	s_waitcnt lgkmcnt(0)
	v_add_f32_e32 v9, v9, v80
	ds_bpermute_b32 v80, v148, v9
	s_waitcnt lgkmcnt(0)
	v_add_f32_e32 v9, v9, v80
	ds_bpermute_b32 v80, v149, v9
	s_and_saveexec_b64 s[2:3], s[0:1]
	s_cbranch_execz .LBB0_4893
	global_load_dwordx4 v[86:89], v[34:35], off
	global_load_dwordx4 v[90:93], v[38:39], off
	global_load_dwordx4 v[94:97], v[40:41], off
	global_load_dwordx4 v[98:101], v[42:43], off
	global_load_dwordx4 v[102:105], v[44:45], off
	global_load_dwordx4 v[106:109], v[46:47], off
	global_load_dwordx4 v[110:113], v[48:49], off
	global_load_dwordx4 v[114:117], v[50:51], off
	global_load_dwordx4 v[118:121], v[36:37], off offset:3072
	global_load_dwordx4 v[122:125], v[32:33], off offset:3072
	global_load_dwordx4 v[126:129], v[32:33], off offset:2048
	global_load_dwordx4 v[130:133], v[36:37], off offset:2048
	global_load_dwordx4 v[134:137], v[36:37], off offset:1024
	global_load_dwordx4 v[138:141], v[32:33], off offset:1024
	global_load_dwordx4 v[142:145], v[32:33], off
	global_load_dwordx4 v[146:149], v[36:37], off
	s_waitcnt lgkmcnt(0)
	v_add_f32_e32 v9, v9, v80
	v_fmamk_f32 v9, v9, 0x3a000000, v165
	v_rsq_f32_e32 v252, v9
	s_nop 1
	s_nop 0
	s_nop 1
	s_nop 1
	s_nop 1
	v_lshlrev_b64 v[80:81], 13, v[56:57]
	v_mov_b32_e32 v56, v252
	v_pk_mul_f32 v[60:61], v[60:61], v[56:57] op_sel_hi:[1,0]
	v_pk_mul_f32 v[58:59], v[58:59], v[56:57] op_sel_hi:[1,0]
	v_pk_mul_f32 v[78:79], v[78:79], v[56:57] op_sel_hi:[1,0]
	v_pk_mul_f32 v[64:65], v[64:65], v[56:57] op_sel_hi:[1,0]
	v_pk_mul_f32 v[76:77], v[76:77], v[56:57] op_sel_hi:[1,0]
	v_pk_mul_f32 v[74:75], v[74:75], v[56:57] op_sel_hi:[1,0]
	v_pk_mul_f32 v[154:155], v[2:3], v[56:57] op_sel_hi:[1,0]
	v_pk_mul_f32 v[156:157], v[0:1], v[56:57] op_sel_hi:[1,0]
	v_pk_mul_f32 v[82:83], v[84:85], v[56:57] op_sel_hi:[1,0]
	v_pk_mul_f32 v[62:63], v[62:63], v[56:57] op_sel_hi:[1,0]
	v_pk_mul_f32 v[66:67], v[66:67], v[56:57] op_sel_hi:[1,0]
	v_pk_mul_f32 v[72:73], v[72:73], v[56:57] op_sel_hi:[1,0]
	v_pk_mul_f32 v[84:85], v[70:71], v[56:57] op_sel_hi:[1,0]
	v_pk_mul_f32 v[68:69], v[68:69], v[56:57] op_sel_hi:[1,0]
	v_pk_mul_f32 v[150:151], v[6:7], v[56:57] op_sel_hi:[1,0]
	v_pk_mul_f32 v[152:153], v[4:5], v[56:57] op_sel_hi:[1,0]
	v_lshl_add_u64 v[80:81], v[52:53], 0, v[80:81]
	s_waitcnt vmcnt(14)
	v_pk_fma_f32 v[2:3], v[92:93], v[58:59], v[88:89]
	v_pk_fma_f32 v[0:1], v[90:91], v[60:61], v[86:87]
	s_waitcnt vmcnt(12)
	v_pk_fma_f32 v[6:7], v[100:101], v[62:63], v[96:97]
	v_pk_fma_f32 v[4:5], v[98:99], v[82:83], v[94:95]
	s_waitcnt vmcnt(10)
	v_pk_fma_f32 v[58:59], v[108:109], v[64:65], v[104:105]
	v_pk_fma_f32 v[56:57], v[106:107], v[78:79], v[102:103]
	s_waitcnt vmcnt(8)
	v_pk_fma_f32 v[60:61], v[114:115], v[76:77], v[110:111]
	v_pk_fma_f32 v[62:63], v[116:117], v[66:67], v[112:113]
	s_waitcnt vmcnt(6)
	v_pk_fma_f32 v[64:65], v[118:119], v[74:75], v[122:123]
	v_pk_fma_f32 v[66:67], v[120:121], v[72:73], v[124:125]
	s_waitcnt vmcnt(4)
	v_pk_fma_f32 v[70:71], v[132:133], v[68:69], v[128:129]
	v_pk_fma_f32 v[68:69], v[130:131], v[84:85], v[126:127]
	s_waitcnt vmcnt(2)
	v_pk_fma_f32 v[74:75], v[136:137], v[152:153], v[140:141]
	v_pk_fma_f32 v[72:73], v[134:135], v[150:151], v[138:139]
	s_waitcnt vmcnt(0)
	v_pk_fma_f32 v[78:79], v[148:149], v[156:157], v[144:145]
	v_pk_fma_f32 v[76:77], v[146:147], v[154:155], v[142:143]
	global_store_dwordx4 v[80:81], v[76:79], off nt
	global_store_dwordx4 v[80:81], v[72:75], off offset:1024 nt
	global_store_dwordx4 v[80:81], v[68:71], off offset:2048 nt
	global_store_dwordx4 v[80:81], v[64:67], off offset:3072 nt
	s_nop 1
	v_add_co_u32_e32 v64, vcc, 0x1000, v80
	s_nop 1
	v_addc_co_u32_e32 v65, vcc, 0, v81, vcc
	global_store_dwordx4 v[64:65], v[60:63], off nt
	global_store_dwordx4 v[64:65], v[56:59], off offset:1024 nt
	global_store_dwordx4 v[64:65], v[4:7], off offset:2048 nt
	global_store_dwordx4 v[64:65], v[0:3], off offset:3072 nt
	s_branch .LBB0_4893
